# merge phase: sample-row gate units also use the prefetched epilogue (partial-sum f32 stores); compiler's serialized path removed
# baseline (speedup 1.0000x reference)
.LBB0_1021:
	s_add_i32 s77, s42, 2
	s_add_u32 s43, s40, 0xfffc0080
	s_addc_u32 s44, s41, -1
	s_add_i32 s78, 0, 0x10000
	v_add_u32_e32 v140, s78, v206
	ds_read_b128 v[128:131], v140
	ds_read_b128 v[132:135], v140 offset:1024
	ds_read_b128 v[136:139], v140 offset:2048
	ds_read_b128 v[140:143], v140 offset:3072
	s_cmp_eq_u32 s74, s42
	s_cselect_b32 s42, s73, s75
	s_cselect_b32 s45, s47, s44
	s_cselect_b32 s44, s54, s43
	s_cselect_b32 s43, s55, s76
	v_lshl_add_u64 v[156:157], s[40:41], 0, v[160:161]
	s_add_i32 m0, s58, 0xc000
	ds_read_b128 v[144:147], v207
	ds_read_b128 v[148:151], v207 offset:1024
	ds_read_b128 v[152:155], v207 offset:2048
	ds_read_b128 v[164:167], v207 offset:3072
	ds_read_b128 v[168:171], v207 offset:4096
	ds_read_b128 v[172:175], v207 offset:5120
	ds_read_b128 v[190:193], v207 offset:6144
	ds_read_b128 v[194:197], v207 offset:7168
	global_load_lds_dwordx4 v[156:157], off
	v_lshl_add_u64 v[156:157], s[40:41], 0, v[162:163]
	s_add_i32 m0, s58, 0xe000
	s_nop 0
	global_load_lds_dwordx4 v[156:157], off
	s_waitcnt lgkmcnt(8)
	s_barrier
	s_waitcnt lgkmcnt(0)
	s_setprio 1
	s_waitcnt lgkmcnt(0)
	v_mfma_f32_16x16x32_bf16 v[124:127], v[128:131], v[144:147], v[124:127]
	v_mfma_f32_16x16x32_bf16 v[120:123], v[136:139], v[144:147], v[120:123]
	v_mfma_f32_16x16x32_bf16 v[116:119], v[128:131], v[152:155], v[116:119]
	v_mfma_f32_16x16x32_bf16 v[112:115], v[136:139], v[152:155], v[112:115]
	v_mfma_f32_16x16x32_bf16 v[108:111], v[128:131], v[168:171], v[108:111]
	v_mfma_f32_16x16x32_bf16 v[104:107], v[136:139], v[168:171], v[104:107]
	v_mfma_f32_16x16x32_bf16 v[100:103], v[128:131], v[190:193], v[100:103]
	v_mfma_f32_16x16x32_bf16 v[96:99], v[136:139], v[190:193], v[96:99]
	v_mfma_f32_16x16x32_bf16 v[124:127], v[132:135], v[148:151], v[124:127]
	v_mfma_f32_16x16x32_bf16 v[120:123], v[140:143], v[148:151], v[120:123]
	v_mfma_f32_16x16x32_bf16 v[116:119], v[132:135], v[164:167], v[116:119]
	v_mfma_f32_16x16x32_bf16 v[112:115], v[140:143], v[164:167], v[112:115]
	v_mfma_f32_16x16x32_bf16 v[108:111], v[132:135], v[172:175], v[108:111]
	v_mfma_f32_16x16x32_bf16 v[104:107], v[140:143], v[172:175], v[104:107]
	v_mfma_f32_16x16x32_bf16 v[100:103], v[132:135], v[194:197], v[100:103]
	v_mfma_f32_16x16x32_bf16 v[96:99], v[140:143], v[194:197], v[96:99]
	s_setprio 0
	s_barrier
	s_add_i32 s80, 0, 0x14000
	v_add_u32_e32 v156, s80, v206
	s_add_i32 s78, s78, s57
	ds_read_b128 v[198:201], v156
	ds_read_b128 v[208:211], v156 offset:1024
	ds_read_b128 v[212:215], v156 offset:2048
	ds_read_b128 v[216:219], v156 offset:3072
	v_lshl_add_u64 v[156:157], s[42:43], 0, v[176:177]
	s_mov_b32 m0, s78
	v_lshl_add_u64 v[202:203], s[42:43], 0, v[158:159]
	global_load_lds_dwordx4 v[156:157], off
	s_add_i32 m0, s78, 0x2000
	s_nop 0
	global_load_lds_dwordx4 v[202:203], off
	s_barrier
	s_waitcnt lgkmcnt(0)
	s_setprio 1
	s_waitcnt lgkmcnt(0)
	v_mfma_f32_16x16x32_bf16 v[92:95], v[198:201], v[144:147], v[92:95]
	v_mfma_f32_16x16x32_bf16 v[88:91], v[212:215], v[144:147], v[88:91]
	v_mfma_f32_16x16x32_bf16 v[84:87], v[198:201], v[152:155], v[84:87]
	v_mfma_f32_16x16x32_bf16 v[80:83], v[212:215], v[152:155], v[80:83]
	v_mfma_f32_16x16x32_bf16 v[76:79], v[198:201], v[168:171], v[76:79]
	v_mfma_f32_16x16x32_bf16 v[72:75], v[212:215], v[168:171], v[72:75]
	v_mfma_f32_16x16x32_bf16 v[68:71], v[198:201], v[190:193], v[68:71]
	v_mfma_f32_16x16x32_bf16 v[64:67], v[212:215], v[190:193], v[64:67]
	v_mfma_f32_16x16x32_bf16 v[92:95], v[208:211], v[148:151], v[92:95]
	v_mfma_f32_16x16x32_bf16 v[88:91], v[216:219], v[148:151], v[88:91]
	v_mfma_f32_16x16x32_bf16 v[84:87], v[208:211], v[164:167], v[84:87]
	v_mfma_f32_16x16x32_bf16 v[80:83], v[216:219], v[164:167], v[80:83]
	v_mfma_f32_16x16x32_bf16 v[76:79], v[208:211], v[172:175], v[76:79]
	v_mfma_f32_16x16x32_bf16 v[72:75], v[216:219], v[172:175], v[72:75]
	v_mfma_f32_16x16x32_bf16 v[68:71], v[208:211], v[194:197], v[68:71]
	v_mfma_f32_16x16x32_bf16 v[64:67], v[216:219], v[194:197], v[64:67]
	s_setprio 0
	s_mov_b32 m0, s58
	v_lshl_add_u64 v[220:221], s[44:45], 0, v[176:177]
	s_barrier
	ds_read_b128 v[144:147], v207 offset:16384
	ds_read_b128 v[148:151], v207 offset:17408
	ds_read_b128 v[152:155], v207 offset:18432
	ds_read_b128 v[164:167], v207 offset:19456
	ds_read_b128 v[168:171], v207 offset:20480
	ds_read_b128 v[172:175], v207 offset:21504
	ds_read_b128 v[190:193], v207 offset:22528
	ds_read_b128 v[194:197], v207 offset:23552
	global_load_lds_dwordx4 v[220:221], off
	v_lshl_add_u64 v[222:223], s[44:45], 0, v[158:159]
	s_mov_b32 m0, s59
	s_nop 0
	global_load_lds_dwordx4 v[222:223], off
	s_barrier
	s_waitcnt lgkmcnt(0)
	s_setprio 1
	s_waitcnt lgkmcnt(0)
	v_mfma_f32_16x16x32_bf16 v[60:63], v[128:131], v[144:147], v[60:63]
	v_mfma_f32_16x16x32_bf16 v[56:59], v[136:139], v[144:147], v[56:59]
	v_mfma_f32_16x16x32_bf16 v[52:55], v[128:131], v[152:155], v[52:55]
	v_mfma_f32_16x16x32_bf16 v[48:51], v[136:139], v[152:155], v[48:51]
	v_mfma_f32_16x16x32_bf16 v[44:47], v[128:131], v[168:171], v[44:47]
	v_mfma_f32_16x16x32_bf16 v[40:43], v[136:139], v[168:171], v[40:43]
	v_mfma_f32_16x16x32_bf16 v[36:39], v[128:131], v[190:193], v[36:39]
	v_mfma_f32_16x16x32_bf16 v[32:35], v[136:139], v[190:193], v[32:35]
	v_mfma_f32_16x16x32_bf16 v[60:63], v[132:135], v[148:151], v[60:63]
	v_mfma_f32_16x16x32_bf16 v[56:59], v[140:143], v[148:151], v[56:59]
	v_mfma_f32_16x16x32_bf16 v[52:55], v[132:135], v[164:167], v[52:55]
	v_mfma_f32_16x16x32_bf16 v[48:51], v[140:143], v[164:167], v[48:51]
	v_mfma_f32_16x16x32_bf16 v[44:47], v[132:135], v[172:175], v[44:47]
	v_mfma_f32_16x16x32_bf16 v[40:43], v[140:143], v[172:175], v[40:43]
	v_mfma_f32_16x16x32_bf16 v[36:39], v[132:135], v[194:197], v[36:39]
	v_mfma_f32_16x16x32_bf16 v[32:35], v[140:143], v[194:197], v[32:35]
	s_setprio 0
	s_barrier
	s_add_u32 s78, s42, 0x40000
	s_addc_u32 s79, s43, 0
	s_add_i32 s80, s80, s57
	v_lshl_add_u64 v[128:129], s[78:79], 0, v[176:177]
	s_mov_b32 m0, s80
	s_nop 0
	global_load_lds_dwordx4 v[128:129], off
	v_lshl_add_u64 v[128:129], s[78:79], 0, v[158:159]
	s_add_i32 m0, s80, 0x2000
	s_nop 0
	global_load_lds_dwordx4 v[128:129], off
	s_waitcnt vmcnt(6)
	s_barrier
	s_setprio 1
	v_mfma_f32_16x16x32_bf16 v[28:31], v[198:201], v[144:147], v[28:31]
	v_mfma_f32_16x16x32_bf16 v[24:27], v[212:215], v[144:147], v[24:27]
	v_mfma_f32_16x16x32_bf16 v[20:23], v[198:201], v[152:155], v[20:23]
	v_mfma_f32_16x16x32_bf16 v[16:19], v[212:215], v[152:155], v[16:19]
	v_mfma_f32_16x16x32_bf16 v[12:15], v[198:201], v[168:171], v[12:15]
	v_mfma_f32_16x16x32_bf16 v[8:11], v[212:215], v[168:171], v[8:11]
	v_mfma_f32_16x16x32_bf16 v[4:7], v[198:201], v[190:193], v[4:7]
	v_mfma_f32_16x16x32_bf16 v[0:3], v[212:215], v[190:193], v[0:3]
	v_mfma_f32_16x16x32_bf16 v[28:31], v[208:211], v[148:151], v[28:31]
	v_mfma_f32_16x16x32_bf16 v[24:27], v[216:219], v[148:151], v[24:27]
	v_mfma_f32_16x16x32_bf16 v[20:23], v[208:211], v[164:167], v[20:23]
	v_mfma_f32_16x16x32_bf16 v[16:19], v[216:219], v[164:167], v[16:19]
	v_mfma_f32_16x16x32_bf16 v[12:15], v[208:211], v[172:175], v[12:15]
	v_mfma_f32_16x16x32_bf16 v[8:11], v[216:219], v[172:175], v[8:11]
	v_mfma_f32_16x16x32_bf16 v[4:7], v[208:211], v[194:197], v[4:7]
	v_mfma_f32_16x16x32_bf16 v[0:3], v[216:219], v[194:197], v[0:3]
	s_setprio 0
	s_add_i32 s78, 0, 0x18000
	v_add_u32_e32 v140, s78, v206
	s_barrier
	ds_read_b128 v[128:131], v140
	ds_read_b128 v[132:135], v140 offset:1024
	ds_read_b128 v[136:139], v140 offset:2048
	ds_read_b128 v[140:143], v140 offset:3072
	s_add_u32 s44, s44, 0x40000
	s_addc_u32 s45, s45, 0
	s_mov_b32 m0, s60
	v_lshl_add_u64 v[198:199], s[44:45], 0, v[176:177]
	ds_read_b128 v[144:147], v207 offset:32768
	ds_read_b128 v[148:151], v207 offset:33792
	ds_read_b128 v[152:155], v207 offset:34816
	ds_read_b128 v[164:167], v207 offset:35840
	ds_read_b128 v[168:171], v207 offset:36864
	ds_read_b128 v[172:175], v207 offset:37888
	ds_read_b128 v[190:193], v207 offset:38912
	ds_read_b128 v[194:197], v207 offset:39936
	global_load_lds_dwordx4 v[198:199], off
	v_lshl_add_u64 v[198:199], s[44:45], 0, v[158:159]
	s_mov_b32 m0, s61
	s_nop 0
	global_load_lds_dwordx4 v[198:199], off
	s_waitcnt lgkmcnt(8)
	s_barrier
	s_waitcnt lgkmcnt(0)
	s_setprio 1
	s_waitcnt lgkmcnt(0)
	v_mfma_f32_16x16x32_bf16 v[124:127], v[128:131], v[144:147], v[124:127]
	v_mfma_f32_16x16x32_bf16 v[120:123], v[136:139], v[144:147], v[120:123]
	v_mfma_f32_16x16x32_bf16 v[116:119], v[128:131], v[152:155], v[116:119]
	v_mfma_f32_16x16x32_bf16 v[112:115], v[136:139], v[152:155], v[112:115]
	v_mfma_f32_16x16x32_bf16 v[108:111], v[128:131], v[168:171], v[108:111]
	v_mfma_f32_16x16x32_bf16 v[104:107], v[136:139], v[168:171], v[104:107]
	v_mfma_f32_16x16x32_bf16 v[100:103], v[128:131], v[190:193], v[100:103]
	v_mfma_f32_16x16x32_bf16 v[96:99], v[136:139], v[190:193], v[96:99]
	v_mfma_f32_16x16x32_bf16 v[124:127], v[132:135], v[148:151], v[124:127]
	v_mfma_f32_16x16x32_bf16 v[120:123], v[140:143], v[148:151], v[120:123]
	v_mfma_f32_16x16x32_bf16 v[116:119], v[132:135], v[164:167], v[116:119]
	v_mfma_f32_16x16x32_bf16 v[112:115], v[140:143], v[164:167], v[112:115]
	v_mfma_f32_16x16x32_bf16 v[108:111], v[132:135], v[172:175], v[108:111]
	v_mfma_f32_16x16x32_bf16 v[104:107], v[140:143], v[172:175], v[104:107]
	v_mfma_f32_16x16x32_bf16 v[100:103], v[132:135], v[194:197], v[100:103]
	v_mfma_f32_16x16x32_bf16 v[96:99], v[140:143], v[194:197], v[96:99]
	s_setprio 0
	s_barrier
	s_add_i32 s44, 0, 0x1c000
	s_add_i32 s45, s78, s57
	v_add_u32_e32 v216, s44, v206
	v_lshl_add_u64 v[156:157], v[156:157], 0, s[24:25]
	s_mov_b32 m0, s45
	ds_read_b128 v[198:201], v216
	ds_read_b128 v[208:211], v216 offset:1024
	ds_read_b128 v[212:215], v216 offset:2048
	ds_read_b128 v[216:219], v216 offset:3072
	global_load_lds_dwordx4 v[156:157], off
	v_lshl_add_u64 v[156:157], v[202:203], 0, s[24:25]
	s_add_i32 m0, s45, 0x2000
	s_nop 0
	global_load_lds_dwordx4 v[156:157], off
	s_barrier
	s_waitcnt lgkmcnt(0)
	s_setprio 1
	s_waitcnt lgkmcnt(0)
	v_mfma_f32_16x16x32_bf16 v[92:95], v[198:201], v[144:147], v[92:95]
	v_mfma_f32_16x16x32_bf16 v[88:91], v[212:215], v[144:147], v[88:91]
	v_mfma_f32_16x16x32_bf16 v[84:87], v[198:201], v[152:155], v[84:87]
	v_mfma_f32_16x16x32_bf16 v[80:83], v[212:215], v[152:155], v[80:83]
	v_mfma_f32_16x16x32_bf16 v[76:79], v[198:201], v[168:171], v[76:79]
	v_mfma_f32_16x16x32_bf16 v[72:75], v[212:215], v[168:171], v[72:75]
	v_mfma_f32_16x16x32_bf16 v[68:71], v[198:201], v[190:193], v[68:71]
	v_mfma_f32_16x16x32_bf16 v[64:67], v[212:215], v[190:193], v[64:67]
	v_mfma_f32_16x16x32_bf16 v[92:95], v[208:211], v[148:151], v[92:95]
	v_mfma_f32_16x16x32_bf16 v[88:91], v[216:219], v[148:151], v[88:91]
	v_mfma_f32_16x16x32_bf16 v[84:87], v[208:211], v[164:167], v[84:87]
	v_mfma_f32_16x16x32_bf16 v[80:83], v[216:219], v[164:167], v[80:83]
	v_mfma_f32_16x16x32_bf16 v[76:79], v[208:211], v[172:175], v[76:79]
	v_mfma_f32_16x16x32_bf16 v[72:75], v[216:219], v[172:175], v[72:75]
	v_mfma_f32_16x16x32_bf16 v[68:71], v[208:211], v[194:197], v[68:71]
	v_mfma_f32_16x16x32_bf16 v[64:67], v[216:219], v[194:197], v[64:67]
	s_setprio 0
	s_mov_b32 m0, s65
	v_lshl_add_u64 v[156:157], v[220:221], 0, s[24:25]
	s_barrier
	ds_read_b128 v[144:147], v207 offset:49152
	ds_read_b128 v[148:151], v207 offset:50176
	ds_read_b128 v[152:155], v207 offset:51200
	ds_read_b128 v[164:167], v207 offset:52224
	ds_read_b128 v[168:171], v207 offset:53248
	ds_read_b128 v[172:175], v207 offset:54272
	ds_read_b128 v[190:193], v207 offset:55296
	ds_read_b128 v[194:197], v207 offset:56320
	global_load_lds_dwordx4 v[156:157], off
	v_lshl_add_u64 v[156:157], v[222:223], 0, s[24:25]
	s_mov_b32 m0, s66
	s_nop 0
	global_load_lds_dwordx4 v[156:157], off
	s_barrier
	s_waitcnt lgkmcnt(0)
	s_setprio 1
	s_waitcnt lgkmcnt(0)
	v_mfma_f32_16x16x32_bf16 v[60:63], v[128:131], v[144:147], v[60:63]
	v_mfma_f32_16x16x32_bf16 v[56:59], v[136:139], v[144:147], v[56:59]
	v_mfma_f32_16x16x32_bf16 v[52:55], v[128:131], v[152:155], v[52:55]
	v_mfma_f32_16x16x32_bf16 v[48:51], v[136:139], v[152:155], v[48:51]
	v_mfma_f32_16x16x32_bf16 v[44:47], v[128:131], v[168:171], v[44:47]
	v_mfma_f32_16x16x32_bf16 v[40:43], v[136:139], v[168:171], v[40:43]
	v_mfma_f32_16x16x32_bf16 v[36:39], v[128:131], v[190:193], v[36:39]
	v_mfma_f32_16x16x32_bf16 v[32:35], v[136:139], v[190:193], v[32:35]
	v_mfma_f32_16x16x32_bf16 v[60:63], v[132:135], v[148:151], v[60:63]
	v_mfma_f32_16x16x32_bf16 v[56:59], v[140:143], v[148:151], v[56:59]
	v_mfma_f32_16x16x32_bf16 v[52:55], v[132:135], v[164:167], v[52:55]
	v_mfma_f32_16x16x32_bf16 v[48:51], v[140:143], v[164:167], v[48:51]
	v_mfma_f32_16x16x32_bf16 v[44:47], v[132:135], v[172:175], v[44:47]
	v_mfma_f32_16x16x32_bf16 v[40:43], v[140:143], v[172:175], v[40:43]
	v_mfma_f32_16x16x32_bf16 v[36:39], v[132:135], v[194:197], v[36:39]
	v_mfma_f32_16x16x32_bf16 v[32:35], v[140:143], v[194:197], v[32:35]
	s_setprio 0
	s_barrier
	s_add_u32 s42, s42, 0x40080
	s_addc_u32 s43, s43, 0
	s_add_i32 s44, s44, s57
	v_lshl_add_u64 v[128:129], s[42:43], 0, v[176:177]
	s_mov_b32 m0, s44
	s_nop 0
	global_load_lds_dwordx4 v[128:129], off
	v_lshl_add_u64 v[128:129], s[42:43], 0, v[158:159]
	s_add_i32 m0, s44, 0x2000
	s_nop 0
	global_load_lds_dwordx4 v[128:129], off
	s_waitcnt vmcnt(6)
	s_barrier
	s_setprio 1
	v_mfma_f32_16x16x32_bf16 v[28:31], v[198:201], v[144:147], v[28:31]
	v_mfma_f32_16x16x32_bf16 v[24:27], v[212:215], v[144:147], v[24:27]
	v_mfma_f32_16x16x32_bf16 v[20:23], v[198:201], v[152:155], v[20:23]
	v_mfma_f32_16x16x32_bf16 v[16:19], v[212:215], v[152:155], v[16:19]
	v_mfma_f32_16x16x32_bf16 v[12:15], v[198:201], v[168:171], v[12:15]
	v_mfma_f32_16x16x32_bf16 v[8:11], v[212:215], v[168:171], v[8:11]
	v_mfma_f32_16x16x32_bf16 v[4:7], v[198:201], v[190:193], v[4:7]
	v_mfma_f32_16x16x32_bf16 v[0:3], v[212:215], v[190:193], v[0:3]
	v_mfma_f32_16x16x32_bf16 v[28:31], v[208:211], v[148:151], v[28:31]
	v_mfma_f32_16x16x32_bf16 v[24:27], v[216:219], v[148:151], v[24:27]
	v_mfma_f32_16x16x32_bf16 v[20:23], v[208:211], v[164:167], v[20:23]
	v_mfma_f32_16x16x32_bf16 v[16:19], v[216:219], v[164:167], v[16:19]
	v_mfma_f32_16x16x32_bf16 v[12:15], v[208:211], v[172:175], v[12:15]
	v_mfma_f32_16x16x32_bf16 v[8:11], v[216:219], v[172:175], v[8:11]
	v_mfma_f32_16x16x32_bf16 v[4:7], v[208:211], v[194:197], v[4:7]
	v_mfma_f32_16x16x32_bf16 v[0:3], v[216:219], v[194:197], v[0:3]
	s_setprio 0
	s_add_u32 s40, s40, 0x100
	s_addc_u32 s41, s41, 0
	s_add_u32 s75, s75, 0x100
	s_addc_u32 s76, s76, 0
	s_cmp_ge_i32 s77, s3
	s_mov_b32 s42, s77
	s_barrier
	s_cbranch_scc0 .LBB0_1021
	v_readlane_b32 s36, v251, 0
	s_mov_b32 s3, s56
	v_mov_b32_e32 v130, v205
	s_mov_b32 s45, s64
	v_mov_b32_e32 v144, v204
	s_mov_b32 s40, s36
	s_ashr_i32 s41, s40, 31
	s_lshl_b64 s[40:41], s[40:41], 17
	s_add_u32 s40, s28, s40
	v_readlane_b32 s37, v249, 19
	s_addc_u32 s41, s37, s41
	v_mov_b32_e32 v128, v224
	s_bitcmp1_b32 s72, 0
	s_cselect_b64 s[54:55], -1, 0
	v_ashrrev_i32_e32 v129, 31, v128
	v_readlane_b32 s76, v250, 37
	v_readlane_b32 s78, v250, 39
	v_lshl_add_u64 v[164:165], v[128:129], 4, s[40:41]
	s_mov_b32 s40, s36
	v_mov_b32_e32 v128, v224
	s_mov_b64 s[42:43], -1
	s_and_b64 vcc, exec, s[54:55]
	v_readlane_b32 s77, v250, 38
	v_readlane_b32 s79, v250, 40
	s_cbranch_vccz .LBB0_1184
	s_ashr_i32 s41, s40, 31
	s_lshl_b64 s[40:41], s[40:41], 17
	v_readlane_b32 s36, v249, 10
	v_readlane_b32 s37, v249, 11
	s_add_u32 s40, s36, s40
	s_addc_u32 s41, s37, s41
	s_cmp_lt_i32 s72, 8
	v_ashrrev_i32_e32 v129, 31, v128
	s_cselect_b64 s[54:55], -1, 0
	s_cmp_gt_i32 s72, 7
	v_lshl_add_u64 v[168:169], v[128:129], 4, s[40:41]
	s_cselect_b64 s[40:41], -1, 0
	s_bfe_u32 s44, s72, 0x20001
	v_lshlrev_b32_e64 v145, 6, s3
	s_lshl_b32 s3, s71, 8
	v_lshlrev_b32_e64 v128, 5, s45
	v_lshlrev_b32_e32 v129, 2, v130
	v_add3_u32 v166, v128, s3, v129
	s_lshl_b32 s3, s44, 12
	s_add_u32 s42, s62, s3
	s_addc_u32 s43, s63, 0
	s_lshl_b32 s2, s2, 8
	v_add3_u32 v172, v144, s2, v145
	v_readlane_b32 s2, v249, 12
	v_ashrrev_i32_e32 v167, 31, v166
	v_ashrrev_i32_e32 v173, 31, v172
	v_readlane_b32 s3, v249, 13
	v_lshl_add_u64 v[128:129], v[166:167], 2, s[42:43]
	s_branch .Lmrg_fast

.Lmrg_fast:
	global_load_dwordx4 v[140:143], v[128:129], off
	global_load_dwordx4 v[136:139], v[128:129], off offset:64
	global_load_dwordx4 v[132:135], v[128:129], off offset:512
	s_nop 0
	global_load_dwordx4 v[128:131], v[128:129], off offset:576
	v_lshl_add_u64 v[246:247], v[172:173], 2, s[2:3]
	v_readfirstlane_b32 s40, v164
	v_readfirstlane_b32 s41, v165
	v_readfirstlane_b32 s42, v168
	v_readfirstlane_b32 s43, v169
	v_readlane_b32 s36, v249, 34
	v_readlane_b32 s37, v249, 35
	global_load_dword v190, v[246:247], off
	global_load_dword v191, v[246:247], off offset:64
	global_load_dword v192, v[246:247], off offset:128
	global_load_dword v193, v[246:247], off offset:192
	global_load_dword v194, v[246:247], off offset:512
	global_load_dword v195, v[246:247], off offset:576
	global_load_dword v196, v[246:247], off offset:640
	global_load_dword v197, v[246:247], off offset:704
	v_lshlrev_b32_e32 v255, 11, v172
	v_lshl_add_u32 v255, v166, 1, v255
	v_subrev_u32_e32 v252, s40, v164
	s_nop 1
	v_mov_b32_e32 v253, v252
	v_mov_b32_e32 v254, 1.0
	s_mov_b32 s45, 0xbfb8aa3b
	s_cmp_lt_i32 s72, 8
	s_cbranch_scc1 .Lmrg_prompt
	s_lshl_b32 s28, s44, 9
	v_add_u32_e32 v255, s28, v172
	v_lshlrev_b32_e32 v255, 12, v255
	v_lshl_add_u32 v255, v166, 2, v255
	s_branch .Lmrg_P
.Lmrg_prompt:
	s_cmp_eq_u32 s44, 0
	s_cbranch_scc1 .Lmrg_b0
	s_cmp_eq_u32 s44, 3
	s_cbranch_scc1 .Lmrg_b3
	global_load_dwordx4 v[144:147], v252, s[40:41]
	global_load_dwordx4 v[148:151], v252, s[42:43]
	v_add_u32_e32 v252, 0x2000, v252
	global_load_dwordx4 v[152:155], v252, s[40:41]
	global_load_dwordx4 v[208:211], v252, s[42:43]
	v_add_u32_e32 v252, 0x2000, v252
	global_load_dwordx4 v[212:215], v252, s[40:41]
	global_load_dwordx4 v[216:219], v252, s[42:43]
	v_add_u32_e32 v252, 0x2000, v252
	global_load_dwordx4 v[220:223], v252, s[40:41]
	global_load_dwordx4 v[240:243], v252, s[42:43]
	v_add_u32_e32 v252, 0x2000, v252
	s_waitcnt vmcnt(6)
	v_mul_f32_e32 v128, s45, v128
	v_mul_f32_e32 v129, s45, v129
	v_mul_f32_e32 v130, s45, v130
	v_mul_f32_e32 v131, s45, v131
	v_mul_f32_e32 v132, s45, v132
	v_mul_f32_e32 v133, s45, v133
	v_mul_f32_e32 v134, s45, v134
	v_mul_f32_e32 v135, s45, v135
	v_mul_f32_e32 v136, s45, v136
	v_mul_f32_e32 v137, s45, v137
	v_mul_f32_e32 v138, s45, v138
	v_mul_f32_e32 v139, s45, v139
	v_mul_f32_e32 v140, s45, v140
	v_mul_f32_e32 v141, s45, v141
	v_mul_f32_e32 v142, s45, v142
	v_mul_f32_e32 v143, s45, v143
	v_fmamk_f32 v239, v190, 0x3a800000, v228
	v_rsq_f32_e32 v238, v239
	v_lshlrev_b32_e32 v164, 16, v144
	v_and_b32_e32 v165, 0xffff0000, v144
	v_lshlrev_b32_e32 v166, 16, v145
	v_and_b32_e32 v167, 0xffff0000, v145
	v_lshlrev_b32_e32 v168, 16, v146
	v_and_b32_e32 v169, 0xffff0000, v146
	v_lshlrev_b32_e32 v170, 16, v147
	v_and_b32_e32 v171, 0xffff0000, v147
	v_mul_f32_e32 v238, s45, v238
	v_lshlrev_b32_e32 v172, 16, v148
	v_and_b32_e32 v173, 0xffff0000, v148
	v_lshlrev_b32_e32 v174, 16, v149
	v_and_b32_e32 v175, 0xffff0000, v149
	v_lshlrev_b32_e32 v156, 16, v150
	v_and_b32_e32 v157, 0xffff0000, v150
	v_lshlrev_b32_e32 v246, 16, v151
	v_and_b32_e32 v247, 0xffff0000, v151
	v_pk_fma_f32 v[198:199], v[124:125], v[238:239], v[140:141] op_sel_hi:[1,0,1]
	v_pk_fma_f32 v[200:201], v[126:127], v[238:239], v[142:143] op_sel_hi:[1,0,1]
	v_pk_fma_f32 v[202:203], v[120:121], v[238:239], v[136:137] op_sel_hi:[1,0,1]
	v_pk_fma_f32 v[244:245], v[122:123], v[238:239], v[138:139] op_sel_hi:[1,0,1]
	global_load_dwordx4 v[124:127], v252, s[40:41]
	global_load_dwordx4 v[120:123], v252, s[42:43]
	v_add_u32_e32 v252, 0x2000, v252
	v_exp_f32_e32 v198, v198
	v_exp_f32_e32 v199, v199
	v_exp_f32_e32 v200, v200
	v_exp_f32_e32 v201, v201
	v_exp_f32_e32 v202, v202
	v_exp_f32_e32 v203, v203
	v_exp_f32_e32 v244, v244
	v_exp_f32_e32 v245, v245
	v_pk_add_f32 v[198:199], v[198:199], v[254:255] op_sel_hi:[1,0]
	v_pk_add_f32 v[200:201], v[200:201], v[254:255] op_sel_hi:[1,0]
	v_pk_add_f32 v[202:203], v[202:203], v[254:255] op_sel_hi:[1,0]
	v_pk_add_f32 v[244:245], v[244:245], v[254:255] op_sel_hi:[1,0]
	v_rcp_f32_e32 v198, v198
	v_rcp_f32_e32 v199, v199
	v_rcp_f32_e32 v200, v200
	v_rcp_f32_e32 v201, v201
	v_rcp_f32_e32 v202, v202
	v_rcp_f32_e32 v203, v203
	v_rcp_f32_e32 v244, v244
	v_rcp_f32_e32 v245, v245
	v_pk_fma_f32 v[198:199], v[198:199], v[164:165], v[172:173]
	v_pk_fma_f32 v[200:201], v[200:201], v[166:167], v[174:175]
	v_pk_fma_f32 v[202:203], v[202:203], v[168:169], v[156:157]
	v_pk_fma_f32 v[244:245], v[244:245], v[170:171], v[246:247]
	v_cvt_pk_bf16_f32 v164, v198, v199
	v_cvt_pk_bf16_f32 v165, v200, v201
	v_cvt_pk_bf16_f32 v166, v202, v203
	v_cvt_pk_bf16_f32 v167, v244, v245
	global_store_dwordx4 v253, v[164:167], s[42:43]
	s_nop 0
	v_add_u32_e32 v253, 0x2000, v253
	s_waitcnt vmcnt(7)
	v_fmamk_f32 v239, v191, 0x3a800000, v228
	v_rsq_f32_e32 v238, v239
	v_lshlrev_b32_e32 v164, 16, v152
	v_and_b32_e32 v165, 0xffff0000, v152
	v_lshlrev_b32_e32 v166, 16, v153
	v_and_b32_e32 v167, 0xffff0000, v153
	v_lshlrev_b32_e32 v168, 16, v154
	v_and_b32_e32 v169, 0xffff0000, v154
	v_lshlrev_b32_e32 v170, 16, v155
	v_and_b32_e32 v171, 0xffff0000, v155
	v_mul_f32_e32 v238, s45, v238
	v_lshlrev_b32_e32 v172, 16, v208
	v_and_b32_e32 v173, 0xffff0000, v208
	v_lshlrev_b32_e32 v174, 16, v209
	v_and_b32_e32 v175, 0xffff0000, v209
	v_lshlrev_b32_e32 v156, 16, v210
	v_and_b32_e32 v157, 0xffff0000, v210
	v_lshlrev_b32_e32 v246, 16, v211
	v_and_b32_e32 v247, 0xffff0000, v211
	v_pk_fma_f32 v[198:199], v[116:117], v[238:239], v[140:141] op_sel_hi:[1,0,1]
	v_pk_fma_f32 v[200:201], v[118:119], v[238:239], v[142:143] op_sel_hi:[1,0,1]
	v_pk_fma_f32 v[202:203], v[112:113], v[238:239], v[136:137] op_sel_hi:[1,0,1]
	v_pk_fma_f32 v[244:245], v[114:115], v[238:239], v[138:139] op_sel_hi:[1,0,1]
	global_load_dwordx4 v[116:119], v252, s[40:41]
	global_load_dwordx4 v[112:115], v252, s[42:43]
	v_add_u32_e32 v252, 0x2000, v252
	v_exp_f32_e32 v198, v198
	v_exp_f32_e32 v199, v199
	v_exp_f32_e32 v200, v200
	v_exp_f32_e32 v201, v201
	v_exp_f32_e32 v202, v202
	v_exp_f32_e32 v203, v203
	v_exp_f32_e32 v244, v244
	v_exp_f32_e32 v245, v245
	v_pk_add_f32 v[198:199], v[198:199], v[254:255] op_sel_hi:[1,0]
	v_pk_add_f32 v[200:201], v[200:201], v[254:255] op_sel_hi:[1,0]
	v_pk_add_f32 v[202:203], v[202:203], v[254:255] op_sel_hi:[1,0]
	v_pk_add_f32 v[244:245], v[244:245], v[254:255] op_sel_hi:[1,0]
	v_rcp_f32_e32 v198, v198
	v_rcp_f32_e32 v199, v199
	v_rcp_f32_e32 v200, v200
	v_rcp_f32_e32 v201, v201
	v_rcp_f32_e32 v202, v202
	v_rcp_f32_e32 v203, v203
	v_rcp_f32_e32 v244, v244
	v_rcp_f32_e32 v245, v245
	v_pk_fma_f32 v[198:199], v[198:199], v[164:165], v[172:173]
	v_pk_fma_f32 v[200:201], v[200:201], v[166:167], v[174:175]
	v_pk_fma_f32 v[202:203], v[202:203], v[168:169], v[156:157]
	v_pk_fma_f32 v[244:245], v[244:245], v[170:171], v[246:247]
	v_cvt_pk_bf16_f32 v164, v198, v199
	v_cvt_pk_bf16_f32 v165, v200, v201
	v_cvt_pk_bf16_f32 v166, v202, v203
	v_cvt_pk_bf16_f32 v167, v244, v245
	global_store_dwordx4 v253, v[164:167], s[42:43]
	s_nop 0
	v_add_u32_e32 v253, 0x2000, v253
	s_waitcnt vmcnt(8)
	v_fmamk_f32 v239, v192, 0x3a800000, v228
	v_rsq_f32_e32 v238, v239
	v_lshlrev_b32_e32 v164, 16, v212
	v_and_b32_e32 v165, 0xffff0000, v212
	v_lshlrev_b32_e32 v166, 16, v213
	v_and_b32_e32 v167, 0xffff0000, v213
	v_lshlrev_b32_e32 v168, 16, v214
	v_and_b32_e32 v169, 0xffff0000, v214
	v_lshlrev_b32_e32 v170, 16, v215
	v_and_b32_e32 v171, 0xffff0000, v215
	v_mul_f32_e32 v238, s45, v238
	v_lshlrev_b32_e32 v172, 16, v216
	v_and_b32_e32 v173, 0xffff0000, v216
	v_lshlrev_b32_e32 v174, 16, v217
	v_and_b32_e32 v175, 0xffff0000, v217
	v_lshlrev_b32_e32 v156, 16, v218
	v_and_b32_e32 v157, 0xffff0000, v218
	v_lshlrev_b32_e32 v246, 16, v219
	v_and_b32_e32 v247, 0xffff0000, v219
	v_pk_fma_f32 v[198:199], v[108:109], v[238:239], v[140:141] op_sel_hi:[1,0,1]
	v_pk_fma_f32 v[200:201], v[110:111], v[238:239], v[142:143] op_sel_hi:[1,0,1]
	v_pk_fma_f32 v[202:203], v[104:105], v[238:239], v[136:137] op_sel_hi:[1,0,1]
	v_pk_fma_f32 v[244:245], v[106:107], v[238:239], v[138:139] op_sel_hi:[1,0,1]
	global_load_dwordx4 v[108:111], v252, s[40:41]
	global_load_dwordx4 v[104:107], v252, s[42:43]
	v_add_u32_e32 v252, 0x2000, v252
	v_exp_f32_e32 v198, v198
	v_exp_f32_e32 v199, v199
	v_exp_f32_e32 v200, v200
	v_exp_f32_e32 v201, v201
	v_exp_f32_e32 v202, v202
	v_exp_f32_e32 v203, v203
	v_exp_f32_e32 v244, v244
	v_exp_f32_e32 v245, v245
	v_pk_add_f32 v[198:199], v[198:199], v[254:255] op_sel_hi:[1,0]
	v_pk_add_f32 v[200:201], v[200:201], v[254:255] op_sel_hi:[1,0]
	v_pk_add_f32 v[202:203], v[202:203], v[254:255] op_sel_hi:[1,0]
	v_pk_add_f32 v[244:245], v[244:245], v[254:255] op_sel_hi:[1,0]
	v_rcp_f32_e32 v198, v198
	v_rcp_f32_e32 v199, v199
	v_rcp_f32_e32 v200, v200
	v_rcp_f32_e32 v201, v201
	v_rcp_f32_e32 v202, v202
	v_rcp_f32_e32 v203, v203
	v_rcp_f32_e32 v244, v244
	v_rcp_f32_e32 v245, v245
	v_pk_fma_f32 v[198:199], v[198:199], v[164:165], v[172:173]
	v_pk_fma_f32 v[200:201], v[200:201], v[166:167], v[174:175]
	v_pk_fma_f32 v[202:203], v[202:203], v[168:169], v[156:157]
	v_pk_fma_f32 v[244:245], v[244:245], v[170:171], v[246:247]
	v_cvt_pk_bf16_f32 v164, v198, v199
	v_cvt_pk_bf16_f32 v165, v200, v201
	v_cvt_pk_bf16_f32 v166, v202, v203
	v_cvt_pk_bf16_f32 v167, v244, v245
	global_store_dwordx4 v253, v[164:167], s[42:43]
	s_nop 0
	v_add_u32_e32 v253, 0x2000, v253
	s_waitcnt vmcnt(9)
	v_fmamk_f32 v239, v193, 0x3a800000, v228
	v_rsq_f32_e32 v238, v239
	v_lshlrev_b32_e32 v164, 16, v220
	v_and_b32_e32 v165, 0xffff0000, v220
	v_lshlrev_b32_e32 v166, 16, v221
	v_and_b32_e32 v167, 0xffff0000, v221
	v_lshlrev_b32_e32 v168, 16, v222
	v_and_b32_e32 v169, 0xffff0000, v222
	v_lshlrev_b32_e32 v170, 16, v223
	v_and_b32_e32 v171, 0xffff0000, v223
	v_mul_f32_e32 v238, s45, v238
	v_lshlrev_b32_e32 v172, 16, v240
	v_and_b32_e32 v173, 0xffff0000, v240
	v_lshlrev_b32_e32 v174, 16, v241
	v_and_b32_e32 v175, 0xffff0000, v241
	v_lshlrev_b32_e32 v156, 16, v242
	v_and_b32_e32 v157, 0xffff0000, v242
	v_lshlrev_b32_e32 v246, 16, v243
	v_and_b32_e32 v247, 0xffff0000, v243
	v_pk_fma_f32 v[198:199], v[100:101], v[238:239], v[140:141] op_sel_hi:[1,0,1]
	v_pk_fma_f32 v[200:201], v[102:103], v[238:239], v[142:143] op_sel_hi:[1,0,1]
	v_pk_fma_f32 v[202:203], v[96:97], v[238:239], v[136:137] op_sel_hi:[1,0,1]
	v_pk_fma_f32 v[244:245], v[98:99], v[238:239], v[138:139] op_sel_hi:[1,0,1]
	global_load_dwordx4 v[100:103], v252, s[40:41]
	global_load_dwordx4 v[96:99], v252, s[42:43]
	v_add_u32_e32 v252, 0x2000, v252
	v_exp_f32_e32 v198, v198
	v_exp_f32_e32 v199, v199
	v_exp_f32_e32 v200, v200
	v_exp_f32_e32 v201, v201
	v_exp_f32_e32 v202, v202
	v_exp_f32_e32 v203, v203
	v_exp_f32_e32 v244, v244
	v_exp_f32_e32 v245, v245
	v_pk_add_f32 v[198:199], v[198:199], v[254:255] op_sel_hi:[1,0]
	v_pk_add_f32 v[200:201], v[200:201], v[254:255] op_sel_hi:[1,0]
	v_pk_add_f32 v[202:203], v[202:203], v[254:255] op_sel_hi:[1,0]
	v_pk_add_f32 v[244:245], v[244:245], v[254:255] op_sel_hi:[1,0]
	v_rcp_f32_e32 v198, v198
	v_rcp_f32_e32 v199, v199
	v_rcp_f32_e32 v200, v200
	v_rcp_f32_e32 v201, v201
	v_rcp_f32_e32 v202, v202
	v_rcp_f32_e32 v203, v203
	v_rcp_f32_e32 v244, v244
	v_rcp_f32_e32 v245, v245
	v_pk_fma_f32 v[198:199], v[198:199], v[164:165], v[172:173]
	v_pk_fma_f32 v[200:201], v[200:201], v[166:167], v[174:175]
	v_pk_fma_f32 v[202:203], v[202:203], v[168:169], v[156:157]
	v_pk_fma_f32 v[244:245], v[244:245], v[170:171], v[246:247]
	v_cvt_pk_bf16_f32 v164, v198, v199
	v_cvt_pk_bf16_f32 v165, v200, v201
	v_cvt_pk_bf16_f32 v166, v202, v203
	v_cvt_pk_bf16_f32 v167, v244, v245
	global_store_dwordx4 v253, v[164:167], s[42:43]
	s_nop 0
	v_add_u32_e32 v253, 0x2000, v253
	s_waitcnt vmcnt(10)
	v_fmamk_f32 v239, v190, 0x3a800000, v228
	v_rsq_f32_e32 v238, v239
	v_lshlrev_b32_e32 v164, 16, v124
	v_and_b32_e32 v165, 0xffff0000, v124
	v_lshlrev_b32_e32 v166, 16, v125
	v_and_b32_e32 v167, 0xffff0000, v125
	v_lshlrev_b32_e32 v168, 16, v126
	v_and_b32_e32 v169, 0xffff0000, v126
	v_lshlrev_b32_e32 v170, 16, v127
	v_and_b32_e32 v171, 0xffff0000, v127
	v_mul_f32_e32 v238, s45, v238
	v_lshlrev_b32_e32 v172, 16, v120
	v_and_b32_e32 v173, 0xffff0000, v120
	v_lshlrev_b32_e32 v174, 16, v121
	v_and_b32_e32 v175, 0xffff0000, v121
	v_lshlrev_b32_e32 v156, 16, v122
	v_and_b32_e32 v157, 0xffff0000, v122
	v_lshlrev_b32_e32 v246, 16, v123
	v_and_b32_e32 v247, 0xffff0000, v123
	v_pk_fma_f32 v[198:199], v[92:93], v[238:239], v[132:133] op_sel_hi:[1,0,1]
	v_pk_fma_f32 v[200:201], v[94:95], v[238:239], v[134:135] op_sel_hi:[1,0,1]
	v_pk_fma_f32 v[202:203], v[88:89], v[238:239], v[128:129] op_sel_hi:[1,0,1]
	v_pk_fma_f32 v[244:245], v[90:91], v[238:239], v[130:131] op_sel_hi:[1,0,1]
	global_load_dwordx4 v[92:95], v252, s[40:41]
	global_load_dwordx4 v[88:91], v252, s[42:43]
	v_add_u32_e32 v252, 0x2000, v252
	v_exp_f32_e32 v198, v198
	v_exp_f32_e32 v199, v199
	v_exp_f32_e32 v200, v200
	v_exp_f32_e32 v201, v201
	v_exp_f32_e32 v202, v202
	v_exp_f32_e32 v203, v203
	v_exp_f32_e32 v244, v244
	v_exp_f32_e32 v245, v245
	v_pk_add_f32 v[198:199], v[198:199], v[254:255] op_sel_hi:[1,0]
	v_pk_add_f32 v[200:201], v[200:201], v[254:255] op_sel_hi:[1,0]
	v_pk_add_f32 v[202:203], v[202:203], v[254:255] op_sel_hi:[1,0]
	v_pk_add_f32 v[244:245], v[244:245], v[254:255] op_sel_hi:[1,0]
	v_rcp_f32_e32 v198, v198
	v_rcp_f32_e32 v199, v199
	v_rcp_f32_e32 v200, v200
	v_rcp_f32_e32 v201, v201
	v_rcp_f32_e32 v202, v202
	v_rcp_f32_e32 v203, v203
	v_rcp_f32_e32 v244, v244
	v_rcp_f32_e32 v245, v245
	v_pk_fma_f32 v[198:199], v[198:199], v[164:165], v[172:173]
	v_pk_fma_f32 v[200:201], v[200:201], v[166:167], v[174:175]
	v_pk_fma_f32 v[202:203], v[202:203], v[168:169], v[156:157]
	v_pk_fma_f32 v[244:245], v[244:245], v[170:171], v[246:247]
	v_cvt_pk_bf16_f32 v164, v198, v199
	v_cvt_pk_bf16_f32 v165, v200, v201
	v_cvt_pk_bf16_f32 v166, v202, v203
	v_cvt_pk_bf16_f32 v167, v244, v245
	global_store_dwordx4 v253, v[164:167], s[42:43]
	s_nop 0
	v_add_u32_e32 v253, 0x2000, v253
	s_waitcnt vmcnt(10)
	v_fmamk_f32 v239, v191, 0x3a800000, v228
	v_rsq_f32_e32 v238, v239
	v_lshlrev_b32_e32 v164, 16, v116
	v_and_b32_e32 v165, 0xffff0000, v116
	v_lshlrev_b32_e32 v166, 16, v117
	v_and_b32_e32 v167, 0xffff0000, v117
	v_lshlrev_b32_e32 v168, 16, v118
	v_and_b32_e32 v169, 0xffff0000, v118
	v_lshlrev_b32_e32 v170, 16, v119
	v_and_b32_e32 v171, 0xffff0000, v119
	v_mul_f32_e32 v238, s45, v238
	v_lshlrev_b32_e32 v172, 16, v112
	v_and_b32_e32 v173, 0xffff0000, v112
	v_lshlrev_b32_e32 v174, 16, v113
	v_and_b32_e32 v175, 0xffff0000, v113
	v_lshlrev_b32_e32 v156, 16, v114
	v_and_b32_e32 v157, 0xffff0000, v114
	v_lshlrev_b32_e32 v246, 16, v115
	v_and_b32_e32 v247, 0xffff0000, v115
	v_pk_fma_f32 v[198:199], v[84:85], v[238:239], v[132:133] op_sel_hi:[1,0,1]
	v_pk_fma_f32 v[200:201], v[86:87], v[238:239], v[134:135] op_sel_hi:[1,0,1]
	v_pk_fma_f32 v[202:203], v[80:81], v[238:239], v[128:129] op_sel_hi:[1,0,1]
	v_pk_fma_f32 v[244:245], v[82:83], v[238:239], v[130:131] op_sel_hi:[1,0,1]
	global_load_dwordx4 v[84:87], v252, s[40:41]
	global_load_dwordx4 v[80:83], v252, s[42:43]
	v_add_u32_e32 v252, 0x2000, v252
	v_exp_f32_e32 v198, v198
	v_exp_f32_e32 v199, v199
	v_exp_f32_e32 v200, v200
	v_exp_f32_e32 v201, v201
	v_exp_f32_e32 v202, v202
	v_exp_f32_e32 v203, v203
	v_exp_f32_e32 v244, v244
	v_exp_f32_e32 v245, v245
	v_pk_add_f32 v[198:199], v[198:199], v[254:255] op_sel_hi:[1,0]
	v_pk_add_f32 v[200:201], v[200:201], v[254:255] op_sel_hi:[1,0]
	v_pk_add_f32 v[202:203], v[202:203], v[254:255] op_sel_hi:[1,0]
	v_pk_add_f32 v[244:245], v[244:245], v[254:255] op_sel_hi:[1,0]
	v_rcp_f32_e32 v198, v198
	v_rcp_f32_e32 v199, v199
	v_rcp_f32_e32 v200, v200
	v_rcp_f32_e32 v201, v201
	v_rcp_f32_e32 v202, v202
	v_rcp_f32_e32 v203, v203
	v_rcp_f32_e32 v244, v244
	v_rcp_f32_e32 v245, v245
	v_pk_fma_f32 v[198:199], v[198:199], v[164:165], v[172:173]
	v_pk_fma_f32 v[200:201], v[200:201], v[166:167], v[174:175]
	v_pk_fma_f32 v[202:203], v[202:203], v[168:169], v[156:157]
	v_pk_fma_f32 v[244:245], v[244:245], v[170:171], v[246:247]
	v_cvt_pk_bf16_f32 v164, v198, v199
	v_cvt_pk_bf16_f32 v165, v200, v201
	v_cvt_pk_bf16_f32 v166, v202, v203
	v_cvt_pk_bf16_f32 v167, v244, v245
	global_store_dwordx4 v253, v[164:167], s[42:43]
	s_nop 0
	v_add_u32_e32 v253, 0x2000, v253
	s_waitcnt vmcnt(10)
	v_fmamk_f32 v239, v192, 0x3a800000, v228
	v_rsq_f32_e32 v238, v239
	v_lshlrev_b32_e32 v164, 16, v108
	v_and_b32_e32 v165, 0xffff0000, v108
	v_lshlrev_b32_e32 v166, 16, v109
	v_and_b32_e32 v167, 0xffff0000, v109
	v_lshlrev_b32_e32 v168, 16, v110
	v_and_b32_e32 v169, 0xffff0000, v110
	v_lshlrev_b32_e32 v170, 16, v111
	v_and_b32_e32 v171, 0xffff0000, v111
	v_mul_f32_e32 v238, s45, v238
	v_lshlrev_b32_e32 v172, 16, v104
	v_and_b32_e32 v173, 0xffff0000, v104
	v_lshlrev_b32_e32 v174, 16, v105
	v_and_b32_e32 v175, 0xffff0000, v105
	v_lshlrev_b32_e32 v156, 16, v106
	v_and_b32_e32 v157, 0xffff0000, v106
	v_lshlrev_b32_e32 v246, 16, v107
	v_and_b32_e32 v247, 0xffff0000, v107
	v_pk_fma_f32 v[198:199], v[76:77], v[238:239], v[132:133] op_sel_hi:[1,0,1]
	v_pk_fma_f32 v[200:201], v[78:79], v[238:239], v[134:135] op_sel_hi:[1,0,1]
	v_pk_fma_f32 v[202:203], v[72:73], v[238:239], v[128:129] op_sel_hi:[1,0,1]
	v_pk_fma_f32 v[244:245], v[74:75], v[238:239], v[130:131] op_sel_hi:[1,0,1]
	global_load_dwordx4 v[76:79], v252, s[40:41]
	global_load_dwordx4 v[72:75], v252, s[42:43]
	v_add_u32_e32 v252, 0x2000, v252
	v_exp_f32_e32 v198, v198
	v_exp_f32_e32 v199, v199
	v_exp_f32_e32 v200, v200
	v_exp_f32_e32 v201, v201
	v_exp_f32_e32 v202, v202
	v_exp_f32_e32 v203, v203
	v_exp_f32_e32 v244, v244
	v_exp_f32_e32 v245, v245
	v_pk_add_f32 v[198:199], v[198:199], v[254:255] op_sel_hi:[1,0]
	v_pk_add_f32 v[200:201], v[200:201], v[254:255] op_sel_hi:[1,0]
	v_pk_add_f32 v[202:203], v[202:203], v[254:255] op_sel_hi:[1,0]
	v_pk_add_f32 v[244:245], v[244:245], v[254:255] op_sel_hi:[1,0]
	v_rcp_f32_e32 v198, v198
	v_rcp_f32_e32 v199, v199
	v_rcp_f32_e32 v200, v200
	v_rcp_f32_e32 v201, v201
	v_rcp_f32_e32 v202, v202
	v_rcp_f32_e32 v203, v203
	v_rcp_f32_e32 v244, v244
	v_rcp_f32_e32 v245, v245
	v_pk_fma_f32 v[198:199], v[198:199], v[164:165], v[172:173]
	v_pk_fma_f32 v[200:201], v[200:201], v[166:167], v[174:175]
	v_pk_fma_f32 v[202:203], v[202:203], v[168:169], v[156:157]
	v_pk_fma_f32 v[244:245], v[244:245], v[170:171], v[246:247]
	v_cvt_pk_bf16_f32 v164, v198, v199
	v_cvt_pk_bf16_f32 v165, v200, v201
	v_cvt_pk_bf16_f32 v166, v202, v203
	v_cvt_pk_bf16_f32 v167, v244, v245
	global_store_dwordx4 v253, v[164:167], s[42:43]
	s_nop 0
	v_add_u32_e32 v253, 0x2000, v253
	s_waitcnt vmcnt(10)
	v_fmamk_f32 v239, v193, 0x3a800000, v228
	v_rsq_f32_e32 v238, v239
	v_lshlrev_b32_e32 v164, 16, v100
	v_and_b32_e32 v165, 0xffff0000, v100
	v_lshlrev_b32_e32 v166, 16, v101
	v_and_b32_e32 v167, 0xffff0000, v101
	v_lshlrev_b32_e32 v168, 16, v102
	v_and_b32_e32 v169, 0xffff0000, v102
	v_lshlrev_b32_e32 v170, 16, v103
	v_and_b32_e32 v171, 0xffff0000, v103
	v_mul_f32_e32 v238, s45, v238
	v_lshlrev_b32_e32 v172, 16, v96
	v_and_b32_e32 v173, 0xffff0000, v96
	v_lshlrev_b32_e32 v174, 16, v97
	v_and_b32_e32 v175, 0xffff0000, v97
	v_lshlrev_b32_e32 v156, 16, v98
	v_and_b32_e32 v157, 0xffff0000, v98
	v_lshlrev_b32_e32 v246, 16, v99
	v_and_b32_e32 v247, 0xffff0000, v99
	v_pk_fma_f32 v[198:199], v[68:69], v[238:239], v[132:133] op_sel_hi:[1,0,1]
	v_pk_fma_f32 v[200:201], v[70:71], v[238:239], v[134:135] op_sel_hi:[1,0,1]
	v_pk_fma_f32 v[202:203], v[64:65], v[238:239], v[128:129] op_sel_hi:[1,0,1]
	v_pk_fma_f32 v[244:245], v[66:67], v[238:239], v[130:131] op_sel_hi:[1,0,1]
	global_load_dwordx4 v[68:71], v252, s[40:41]
	global_load_dwordx4 v[64:67], v252, s[42:43]
	v_add_u32_e32 v252, 0x2000, v252
	v_exp_f32_e32 v198, v198
	v_exp_f32_e32 v199, v199
	v_exp_f32_e32 v200, v200
	v_exp_f32_e32 v201, v201
	v_exp_f32_e32 v202, v202
	v_exp_f32_e32 v203, v203
	v_exp_f32_e32 v244, v244
	v_exp_f32_e32 v245, v245
	v_pk_add_f32 v[198:199], v[198:199], v[254:255] op_sel_hi:[1,0]
	v_pk_add_f32 v[200:201], v[200:201], v[254:255] op_sel_hi:[1,0]
	v_pk_add_f32 v[202:203], v[202:203], v[254:255] op_sel_hi:[1,0]
	v_pk_add_f32 v[244:245], v[244:245], v[254:255] op_sel_hi:[1,0]
	v_rcp_f32_e32 v198, v198
	v_rcp_f32_e32 v199, v199
	v_rcp_f32_e32 v200, v200
	v_rcp_f32_e32 v201, v201
	v_rcp_f32_e32 v202, v202
	v_rcp_f32_e32 v203, v203
	v_rcp_f32_e32 v244, v244
	v_rcp_f32_e32 v245, v245
	v_pk_fma_f32 v[198:199], v[198:199], v[164:165], v[172:173]
	v_pk_fma_f32 v[200:201], v[200:201], v[166:167], v[174:175]
	v_pk_fma_f32 v[202:203], v[202:203], v[168:169], v[156:157]
	v_pk_fma_f32 v[244:245], v[244:245], v[170:171], v[246:247]
	v_cvt_pk_bf16_f32 v164, v198, v199
	v_cvt_pk_bf16_f32 v165, v200, v201
	v_cvt_pk_bf16_f32 v166, v202, v203
	v_cvt_pk_bf16_f32 v167, v244, v245
	global_store_dwordx4 v253, v[164:167], s[42:43]
	s_nop 0
	v_add_u32_e32 v253, 0x2000, v253
	s_waitcnt vmcnt(10)
	v_fmamk_f32 v239, v194, 0x3a800000, v228
	v_rsq_f32_e32 v238, v239
	v_lshlrev_b32_e32 v164, 16, v92
	v_and_b32_e32 v165, 0xffff0000, v92
	v_lshlrev_b32_e32 v166, 16, v93
	v_and_b32_e32 v167, 0xffff0000, v93
	v_lshlrev_b32_e32 v168, 16, v94
	v_and_b32_e32 v169, 0xffff0000, v94
	v_lshlrev_b32_e32 v170, 16, v95
	v_and_b32_e32 v171, 0xffff0000, v95
	v_mul_f32_e32 v238, s45, v238
	v_lshlrev_b32_e32 v172, 16, v88
	v_and_b32_e32 v173, 0xffff0000, v88
	v_lshlrev_b32_e32 v174, 16, v89
	v_and_b32_e32 v175, 0xffff0000, v89
	v_lshlrev_b32_e32 v156, 16, v90
	v_and_b32_e32 v157, 0xffff0000, v90
	v_lshlrev_b32_e32 v246, 16, v91
	v_and_b32_e32 v247, 0xffff0000, v91
	v_pk_fma_f32 v[198:199], v[60:61], v[238:239], v[140:141] op_sel_hi:[1,0,1]
	v_pk_fma_f32 v[200:201], v[62:63], v[238:239], v[142:143] op_sel_hi:[1,0,1]
	v_pk_fma_f32 v[202:203], v[56:57], v[238:239], v[136:137] op_sel_hi:[1,0,1]
	v_pk_fma_f32 v[244:245], v[58:59], v[238:239], v[138:139] op_sel_hi:[1,0,1]
	global_load_dwordx4 v[60:63], v252, s[40:41]
	global_load_dwordx4 v[56:59], v252, s[42:43]
	v_add_u32_e32 v252, 0x2000, v252
	v_exp_f32_e32 v198, v198
	v_exp_f32_e32 v199, v199
	v_exp_f32_e32 v200, v200
	v_exp_f32_e32 v201, v201
	v_exp_f32_e32 v202, v202
	v_exp_f32_e32 v203, v203
	v_exp_f32_e32 v244, v244
	v_exp_f32_e32 v245, v245
	v_pk_add_f32 v[198:199], v[198:199], v[254:255] op_sel_hi:[1,0]
	v_pk_add_f32 v[200:201], v[200:201], v[254:255] op_sel_hi:[1,0]
	v_pk_add_f32 v[202:203], v[202:203], v[254:255] op_sel_hi:[1,0]
	v_pk_add_f32 v[244:245], v[244:245], v[254:255] op_sel_hi:[1,0]
	v_rcp_f32_e32 v198, v198
	v_rcp_f32_e32 v199, v199
	v_rcp_f32_e32 v200, v200
	v_rcp_f32_e32 v201, v201
	v_rcp_f32_e32 v202, v202
	v_rcp_f32_e32 v203, v203
	v_rcp_f32_e32 v244, v244
	v_rcp_f32_e32 v245, v245
	v_pk_fma_f32 v[198:199], v[198:199], v[164:165], v[172:173]
	v_pk_fma_f32 v[200:201], v[200:201], v[166:167], v[174:175]
	v_pk_fma_f32 v[202:203], v[202:203], v[168:169], v[156:157]
	v_pk_fma_f32 v[244:245], v[244:245], v[170:171], v[246:247]
	v_cvt_pk_bf16_f32 v164, v198, v199
	v_cvt_pk_bf16_f32 v165, v200, v201
	v_cvt_pk_bf16_f32 v166, v202, v203
	v_cvt_pk_bf16_f32 v167, v244, v245
	global_store_dwordx4 v253, v[164:167], s[42:43]
	s_nop 0
	v_add_u32_e32 v253, 0x2000, v253
	s_waitcnt vmcnt(10)
	v_fmamk_f32 v239, v195, 0x3a800000, v228
	v_rsq_f32_e32 v238, v239
	v_lshlrev_b32_e32 v164, 16, v84
	v_and_b32_e32 v165, 0xffff0000, v84
	v_lshlrev_b32_e32 v166, 16, v85
	v_and_b32_e32 v167, 0xffff0000, v85
	v_lshlrev_b32_e32 v168, 16, v86
	v_and_b32_e32 v169, 0xffff0000, v86
	v_lshlrev_b32_e32 v170, 16, v87
	v_and_b32_e32 v171, 0xffff0000, v87
	v_mul_f32_e32 v238, s45, v238
	v_lshlrev_b32_e32 v172, 16, v80
	v_and_b32_e32 v173, 0xffff0000, v80
	v_lshlrev_b32_e32 v174, 16, v81
	v_and_b32_e32 v175, 0xffff0000, v81
	v_lshlrev_b32_e32 v156, 16, v82
	v_and_b32_e32 v157, 0xffff0000, v82
	v_lshlrev_b32_e32 v246, 16, v83
	v_and_b32_e32 v247, 0xffff0000, v83
	v_pk_fma_f32 v[198:199], v[52:53], v[238:239], v[140:141] op_sel_hi:[1,0,1]
	v_pk_fma_f32 v[200:201], v[54:55], v[238:239], v[142:143] op_sel_hi:[1,0,1]
	v_pk_fma_f32 v[202:203], v[48:49], v[238:239], v[136:137] op_sel_hi:[1,0,1]
	v_pk_fma_f32 v[244:245], v[50:51], v[238:239], v[138:139] op_sel_hi:[1,0,1]
	global_load_dwordx4 v[52:55], v252, s[40:41]
	global_load_dwordx4 v[48:51], v252, s[42:43]
	v_add_u32_e32 v252, 0x2000, v252
	v_exp_f32_e32 v198, v198
	v_exp_f32_e32 v199, v199
	v_exp_f32_e32 v200, v200
	v_exp_f32_e32 v201, v201
	v_exp_f32_e32 v202, v202
	v_exp_f32_e32 v203, v203
	v_exp_f32_e32 v244, v244
	v_exp_f32_e32 v245, v245
	v_pk_add_f32 v[198:199], v[198:199], v[254:255] op_sel_hi:[1,0]
	v_pk_add_f32 v[200:201], v[200:201], v[254:255] op_sel_hi:[1,0]
	v_pk_add_f32 v[202:203], v[202:203], v[254:255] op_sel_hi:[1,0]
	v_pk_add_f32 v[244:245], v[244:245], v[254:255] op_sel_hi:[1,0]
	v_rcp_f32_e32 v198, v198
	v_rcp_f32_e32 v199, v199
	v_rcp_f32_e32 v200, v200
	v_rcp_f32_e32 v201, v201
	v_rcp_f32_e32 v202, v202
	v_rcp_f32_e32 v203, v203
	v_rcp_f32_e32 v244, v244
	v_rcp_f32_e32 v245, v245
	v_pk_fma_f32 v[198:199], v[198:199], v[164:165], v[172:173]
	v_pk_fma_f32 v[200:201], v[200:201], v[166:167], v[174:175]
	v_pk_fma_f32 v[202:203], v[202:203], v[168:169], v[156:157]
	v_pk_fma_f32 v[244:245], v[244:245], v[170:171], v[246:247]
	v_cvt_pk_bf16_f32 v164, v198, v199
	v_cvt_pk_bf16_f32 v165, v200, v201
	v_cvt_pk_bf16_f32 v166, v202, v203
	v_cvt_pk_bf16_f32 v167, v244, v245
	global_store_dwordx4 v253, v[164:167], s[42:43]
	s_nop 0
	v_add_u32_e32 v253, 0x2000, v253
	s_waitcnt vmcnt(10)
	v_fmamk_f32 v239, v196, 0x3a800000, v228
	v_rsq_f32_e32 v238, v239
	v_lshlrev_b32_e32 v164, 16, v76
	v_and_b32_e32 v165, 0xffff0000, v76
	v_lshlrev_b32_e32 v166, 16, v77
	v_and_b32_e32 v167, 0xffff0000, v77
	v_lshlrev_b32_e32 v168, 16, v78
	v_and_b32_e32 v169, 0xffff0000, v78
	v_lshlrev_b32_e32 v170, 16, v79
	v_and_b32_e32 v171, 0xffff0000, v79
	v_mul_f32_e32 v238, s45, v238
	v_lshlrev_b32_e32 v172, 16, v72
	v_and_b32_e32 v173, 0xffff0000, v72
	v_lshlrev_b32_e32 v174, 16, v73
	v_and_b32_e32 v175, 0xffff0000, v73
	v_lshlrev_b32_e32 v156, 16, v74
	v_and_b32_e32 v157, 0xffff0000, v74
	v_lshlrev_b32_e32 v246, 16, v75
	v_and_b32_e32 v247, 0xffff0000, v75
	v_pk_fma_f32 v[198:199], v[44:45], v[238:239], v[140:141] op_sel_hi:[1,0,1]
	v_pk_fma_f32 v[200:201], v[46:47], v[238:239], v[142:143] op_sel_hi:[1,0,1]
	v_pk_fma_f32 v[202:203], v[40:41], v[238:239], v[136:137] op_sel_hi:[1,0,1]
	v_pk_fma_f32 v[244:245], v[42:43], v[238:239], v[138:139] op_sel_hi:[1,0,1]
	global_load_dwordx4 v[44:47], v252, s[40:41]
	global_load_dwordx4 v[40:43], v252, s[42:43]
	v_add_u32_e32 v252, 0x2000, v252
	v_exp_f32_e32 v198, v198
	v_exp_f32_e32 v199, v199
	v_exp_f32_e32 v200, v200
	v_exp_f32_e32 v201, v201
	v_exp_f32_e32 v202, v202
	v_exp_f32_e32 v203, v203
	v_exp_f32_e32 v244, v244
	v_exp_f32_e32 v245, v245
	v_pk_add_f32 v[198:199], v[198:199], v[254:255] op_sel_hi:[1,0]
	v_pk_add_f32 v[200:201], v[200:201], v[254:255] op_sel_hi:[1,0]
	v_pk_add_f32 v[202:203], v[202:203], v[254:255] op_sel_hi:[1,0]
	v_pk_add_f32 v[244:245], v[244:245], v[254:255] op_sel_hi:[1,0]
	v_rcp_f32_e32 v198, v198
	v_rcp_f32_e32 v199, v199
	v_rcp_f32_e32 v200, v200
	v_rcp_f32_e32 v201, v201
	v_rcp_f32_e32 v202, v202
	v_rcp_f32_e32 v203, v203
	v_rcp_f32_e32 v244, v244
	v_rcp_f32_e32 v245, v245
	v_pk_fma_f32 v[198:199], v[198:199], v[164:165], v[172:173]
	v_pk_fma_f32 v[200:201], v[200:201], v[166:167], v[174:175]
	v_pk_fma_f32 v[202:203], v[202:203], v[168:169], v[156:157]
	v_pk_fma_f32 v[244:245], v[244:245], v[170:171], v[246:247]
	v_cvt_pk_bf16_f32 v164, v198, v199
	v_cvt_pk_bf16_f32 v165, v200, v201
	v_cvt_pk_bf16_f32 v166, v202, v203
	v_cvt_pk_bf16_f32 v167, v244, v245
	global_store_dwordx4 v253, v[164:167], s[42:43]
	s_nop 0
	v_add_u32_e32 v253, 0x2000, v253
	s_waitcnt vmcnt(10)
	v_fmamk_f32 v239, v197, 0x3a800000, v228
	v_rsq_f32_e32 v238, v239
	v_lshlrev_b32_e32 v164, 16, v68
	v_and_b32_e32 v165, 0xffff0000, v68
	v_lshlrev_b32_e32 v166, 16, v69
	v_and_b32_e32 v167, 0xffff0000, v69
	v_lshlrev_b32_e32 v168, 16, v70
	v_and_b32_e32 v169, 0xffff0000, v70
	v_lshlrev_b32_e32 v170, 16, v71
	v_and_b32_e32 v171, 0xffff0000, v71
	v_mul_f32_e32 v238, s45, v238
	v_lshlrev_b32_e32 v172, 16, v64
	v_and_b32_e32 v173, 0xffff0000, v64
	v_lshlrev_b32_e32 v174, 16, v65
	v_and_b32_e32 v175, 0xffff0000, v65
	v_lshlrev_b32_e32 v156, 16, v66
	v_and_b32_e32 v157, 0xffff0000, v66
	v_lshlrev_b32_e32 v246, 16, v67
	v_and_b32_e32 v247, 0xffff0000, v67
	v_pk_fma_f32 v[198:199], v[36:37], v[238:239], v[140:141] op_sel_hi:[1,0,1]
	v_pk_fma_f32 v[200:201], v[38:39], v[238:239], v[142:143] op_sel_hi:[1,0,1]
	v_pk_fma_f32 v[202:203], v[32:33], v[238:239], v[136:137] op_sel_hi:[1,0,1]
	v_pk_fma_f32 v[244:245], v[34:35], v[238:239], v[138:139] op_sel_hi:[1,0,1]
	global_load_dwordx4 v[36:39], v252, s[40:41]
	global_load_dwordx4 v[32:35], v252, s[42:43]
	v_add_u32_e32 v252, 0x2000, v252
	v_exp_f32_e32 v198, v198
	v_exp_f32_e32 v199, v199
	v_exp_f32_e32 v200, v200
	v_exp_f32_e32 v201, v201
	v_exp_f32_e32 v202, v202
	v_exp_f32_e32 v203, v203
	v_exp_f32_e32 v244, v244
	v_exp_f32_e32 v245, v245
	v_pk_add_f32 v[198:199], v[198:199], v[254:255] op_sel_hi:[1,0]
	v_pk_add_f32 v[200:201], v[200:201], v[254:255] op_sel_hi:[1,0]
	v_pk_add_f32 v[202:203], v[202:203], v[254:255] op_sel_hi:[1,0]
	v_pk_add_f32 v[244:245], v[244:245], v[254:255] op_sel_hi:[1,0]
	v_rcp_f32_e32 v198, v198
	v_rcp_f32_e32 v199, v199
	v_rcp_f32_e32 v200, v200
	v_rcp_f32_e32 v201, v201
	v_rcp_f32_e32 v202, v202
	v_rcp_f32_e32 v203, v203
	v_rcp_f32_e32 v244, v244
	v_rcp_f32_e32 v245, v245
	v_pk_fma_f32 v[198:199], v[198:199], v[164:165], v[172:173]
	v_pk_fma_f32 v[200:201], v[200:201], v[166:167], v[174:175]
	v_pk_fma_f32 v[202:203], v[202:203], v[168:169], v[156:157]
	v_pk_fma_f32 v[244:245], v[244:245], v[170:171], v[246:247]
	v_cvt_pk_bf16_f32 v164, v198, v199
	v_cvt_pk_bf16_f32 v165, v200, v201
	v_cvt_pk_bf16_f32 v166, v202, v203
	v_cvt_pk_bf16_f32 v167, v244, v245
	global_store_dwordx4 v253, v[164:167], s[42:43]
	s_nop 0
	v_add_u32_e32 v253, 0x2000, v253
	s_waitcnt vmcnt(10)
	v_fmamk_f32 v239, v194, 0x3a800000, v228
	v_rsq_f32_e32 v238, v239
	v_lshlrev_b32_e32 v164, 16, v60
	v_and_b32_e32 v165, 0xffff0000, v60
	v_lshlrev_b32_e32 v166, 16, v61
	v_and_b32_e32 v167, 0xffff0000, v61
	v_lshlrev_b32_e32 v168, 16, v62
	v_and_b32_e32 v169, 0xffff0000, v62
	v_lshlrev_b32_e32 v170, 16, v63
	v_and_b32_e32 v171, 0xffff0000, v63
	v_mul_f32_e32 v238, s45, v238
	v_lshlrev_b32_e32 v172, 16, v56
	v_and_b32_e32 v173, 0xffff0000, v56
	v_lshlrev_b32_e32 v174, 16, v57
	v_and_b32_e32 v175, 0xffff0000, v57
	v_lshlrev_b32_e32 v156, 16, v58
	v_and_b32_e32 v157, 0xffff0000, v58
	v_lshlrev_b32_e32 v246, 16, v59
	v_and_b32_e32 v247, 0xffff0000, v59
	v_pk_fma_f32 v[198:199], v[28:29], v[238:239], v[132:133] op_sel_hi:[1,0,1]
	v_pk_fma_f32 v[200:201], v[30:31], v[238:239], v[134:135] op_sel_hi:[1,0,1]
	v_pk_fma_f32 v[202:203], v[24:25], v[238:239], v[128:129] op_sel_hi:[1,0,1]
	v_pk_fma_f32 v[244:245], v[26:27], v[238:239], v[130:131] op_sel_hi:[1,0,1]
	v_exp_f32_e32 v198, v198
	v_exp_f32_e32 v199, v199
	v_exp_f32_e32 v200, v200
	v_exp_f32_e32 v201, v201
	v_exp_f32_e32 v202, v202
	v_exp_f32_e32 v203, v203
	v_exp_f32_e32 v244, v244
	v_exp_f32_e32 v245, v245
	v_pk_add_f32 v[198:199], v[198:199], v[254:255] op_sel_hi:[1,0]
	v_pk_add_f32 v[200:201], v[200:201], v[254:255] op_sel_hi:[1,0]
	v_pk_add_f32 v[202:203], v[202:203], v[254:255] op_sel_hi:[1,0]
	v_pk_add_f32 v[244:245], v[244:245], v[254:255] op_sel_hi:[1,0]
	v_rcp_f32_e32 v198, v198
	v_rcp_f32_e32 v199, v199
	v_rcp_f32_e32 v200, v200
	v_rcp_f32_e32 v201, v201
	v_rcp_f32_e32 v202, v202
	v_rcp_f32_e32 v203, v203
	v_rcp_f32_e32 v244, v244
	v_rcp_f32_e32 v245, v245
	v_pk_fma_f32 v[198:199], v[198:199], v[164:165], v[172:173]
	v_pk_fma_f32 v[200:201], v[200:201], v[166:167], v[174:175]
	v_pk_fma_f32 v[202:203], v[202:203], v[168:169], v[156:157]
	v_pk_fma_f32 v[244:245], v[244:245], v[170:171], v[246:247]
	v_cvt_pk_bf16_f32 v164, v198, v199
	v_cvt_pk_bf16_f32 v165, v200, v201
	v_cvt_pk_bf16_f32 v166, v202, v203
	v_cvt_pk_bf16_f32 v167, v244, v245
	global_store_dwordx4 v253, v[164:167], s[42:43]
	s_nop 0
	v_add_u32_e32 v253, 0x2000, v253
	s_waitcnt vmcnt(8)
	v_fmamk_f32 v239, v195, 0x3a800000, v228
	v_rsq_f32_e32 v238, v239
	v_lshlrev_b32_e32 v164, 16, v52
	v_and_b32_e32 v165, 0xffff0000, v52
	v_lshlrev_b32_e32 v166, 16, v53
	v_and_b32_e32 v167, 0xffff0000, v53
	v_lshlrev_b32_e32 v168, 16, v54
	v_and_b32_e32 v169, 0xffff0000, v54
	v_lshlrev_b32_e32 v170, 16, v55
	v_and_b32_e32 v171, 0xffff0000, v55
	v_mul_f32_e32 v238, s45, v238
	v_lshlrev_b32_e32 v172, 16, v48
	v_and_b32_e32 v173, 0xffff0000, v48
	v_lshlrev_b32_e32 v174, 16, v49
	v_and_b32_e32 v175, 0xffff0000, v49
	v_lshlrev_b32_e32 v156, 16, v50
	v_and_b32_e32 v157, 0xffff0000, v50
	v_lshlrev_b32_e32 v246, 16, v51
	v_and_b32_e32 v247, 0xffff0000, v51
	v_pk_fma_f32 v[198:199], v[20:21], v[238:239], v[132:133] op_sel_hi:[1,0,1]
	v_pk_fma_f32 v[200:201], v[22:23], v[238:239], v[134:135] op_sel_hi:[1,0,1]
	v_pk_fma_f32 v[202:203], v[16:17], v[238:239], v[128:129] op_sel_hi:[1,0,1]
	v_pk_fma_f32 v[244:245], v[18:19], v[238:239], v[130:131] op_sel_hi:[1,0,1]
	v_exp_f32_e32 v198, v198
	v_exp_f32_e32 v199, v199
	v_exp_f32_e32 v200, v200
	v_exp_f32_e32 v201, v201
	v_exp_f32_e32 v202, v202
	v_exp_f32_e32 v203, v203
	v_exp_f32_e32 v244, v244
	v_exp_f32_e32 v245, v245
	v_pk_add_f32 v[198:199], v[198:199], v[254:255] op_sel_hi:[1,0]
	v_pk_add_f32 v[200:201], v[200:201], v[254:255] op_sel_hi:[1,0]
	v_pk_add_f32 v[202:203], v[202:203], v[254:255] op_sel_hi:[1,0]
	v_pk_add_f32 v[244:245], v[244:245], v[254:255] op_sel_hi:[1,0]
	v_rcp_f32_e32 v198, v198
	v_rcp_f32_e32 v199, v199
	v_rcp_f32_e32 v200, v200
	v_rcp_f32_e32 v201, v201
	v_rcp_f32_e32 v202, v202
	v_rcp_f32_e32 v203, v203
	v_rcp_f32_e32 v244, v244
	v_rcp_f32_e32 v245, v245
	v_pk_fma_f32 v[198:199], v[198:199], v[164:165], v[172:173]
	v_pk_fma_f32 v[200:201], v[200:201], v[166:167], v[174:175]
	v_pk_fma_f32 v[202:203], v[202:203], v[168:169], v[156:157]
	v_pk_fma_f32 v[244:245], v[244:245], v[170:171], v[246:247]
	v_cvt_pk_bf16_f32 v164, v198, v199
	v_cvt_pk_bf16_f32 v165, v200, v201
	v_cvt_pk_bf16_f32 v166, v202, v203
	v_cvt_pk_bf16_f32 v167, v244, v245
	global_store_dwordx4 v253, v[164:167], s[42:43]
	s_nop 0
	v_add_u32_e32 v253, 0x2000, v253
	s_waitcnt vmcnt(6)
	v_fmamk_f32 v239, v196, 0x3a800000, v228
	v_rsq_f32_e32 v238, v239
	v_lshlrev_b32_e32 v164, 16, v44
	v_and_b32_e32 v165, 0xffff0000, v44
	v_lshlrev_b32_e32 v166, 16, v45
	v_and_b32_e32 v167, 0xffff0000, v45
	v_lshlrev_b32_e32 v168, 16, v46
	v_and_b32_e32 v169, 0xffff0000, v46
	v_lshlrev_b32_e32 v170, 16, v47
	v_and_b32_e32 v171, 0xffff0000, v47
	v_mul_f32_e32 v238, s45, v238
	v_lshlrev_b32_e32 v172, 16, v40
	v_and_b32_e32 v173, 0xffff0000, v40
	v_lshlrev_b32_e32 v174, 16, v41
	v_and_b32_e32 v175, 0xffff0000, v41
	v_lshlrev_b32_e32 v156, 16, v42
	v_and_b32_e32 v157, 0xffff0000, v42
	v_lshlrev_b32_e32 v246, 16, v43
	v_and_b32_e32 v247, 0xffff0000, v43
	v_pk_fma_f32 v[198:199], v[12:13], v[238:239], v[132:133] op_sel_hi:[1,0,1]
	v_pk_fma_f32 v[200:201], v[14:15], v[238:239], v[134:135] op_sel_hi:[1,0,1]
	v_pk_fma_f32 v[202:203], v[8:9], v[238:239], v[128:129] op_sel_hi:[1,0,1]
	v_pk_fma_f32 v[244:245], v[10:11], v[238:239], v[130:131] op_sel_hi:[1,0,1]
	v_exp_f32_e32 v198, v198
	v_exp_f32_e32 v199, v199
	v_exp_f32_e32 v200, v200
	v_exp_f32_e32 v201, v201
	v_exp_f32_e32 v202, v202
	v_exp_f32_e32 v203, v203
	v_exp_f32_e32 v244, v244
	v_exp_f32_e32 v245, v245
	v_pk_add_f32 v[198:199], v[198:199], v[254:255] op_sel_hi:[1,0]
	v_pk_add_f32 v[200:201], v[200:201], v[254:255] op_sel_hi:[1,0]
	v_pk_add_f32 v[202:203], v[202:203], v[254:255] op_sel_hi:[1,0]
	v_pk_add_f32 v[244:245], v[244:245], v[254:255] op_sel_hi:[1,0]
	v_rcp_f32_e32 v198, v198
	v_rcp_f32_e32 v199, v199
	v_rcp_f32_e32 v200, v200
	v_rcp_f32_e32 v201, v201
	v_rcp_f32_e32 v202, v202
	v_rcp_f32_e32 v203, v203
	v_rcp_f32_e32 v244, v244
	v_rcp_f32_e32 v245, v245
	v_pk_fma_f32 v[198:199], v[198:199], v[164:165], v[172:173]
	v_pk_fma_f32 v[200:201], v[200:201], v[166:167], v[174:175]
	v_pk_fma_f32 v[202:203], v[202:203], v[168:169], v[156:157]
	v_pk_fma_f32 v[244:245], v[244:245], v[170:171], v[246:247]
	v_cvt_pk_bf16_f32 v164, v198, v199
	v_cvt_pk_bf16_f32 v165, v200, v201
	v_cvt_pk_bf16_f32 v166, v202, v203
	v_cvt_pk_bf16_f32 v167, v244, v245
	global_store_dwordx4 v253, v[164:167], s[42:43]
	s_nop 0
	v_add_u32_e32 v253, 0x2000, v253
	s_waitcnt vmcnt(4)
	v_fmamk_f32 v239, v197, 0x3a800000, v228
	v_rsq_f32_e32 v238, v239
	v_lshlrev_b32_e32 v164, 16, v36
	v_and_b32_e32 v165, 0xffff0000, v36
	v_lshlrev_b32_e32 v166, 16, v37
	v_and_b32_e32 v167, 0xffff0000, v37
	v_lshlrev_b32_e32 v168, 16, v38
	v_and_b32_e32 v169, 0xffff0000, v38
	v_lshlrev_b32_e32 v170, 16, v39
	v_and_b32_e32 v171, 0xffff0000, v39
	v_mul_f32_e32 v238, s45, v238
	v_lshlrev_b32_e32 v172, 16, v32
	v_and_b32_e32 v173, 0xffff0000, v32
	v_lshlrev_b32_e32 v174, 16, v33
	v_and_b32_e32 v175, 0xffff0000, v33
	v_lshlrev_b32_e32 v156, 16, v34
	v_and_b32_e32 v157, 0xffff0000, v34
	v_lshlrev_b32_e32 v246, 16, v35
	v_and_b32_e32 v247, 0xffff0000, v35
	v_pk_fma_f32 v[198:199], v[4:5], v[238:239], v[132:133] op_sel_hi:[1,0,1]
	v_pk_fma_f32 v[200:201], v[6:7], v[238:239], v[134:135] op_sel_hi:[1,0,1]
	v_pk_fma_f32 v[202:203], v[0:1], v[238:239], v[128:129] op_sel_hi:[1,0,1]
	v_pk_fma_f32 v[244:245], v[2:3], v[238:239], v[130:131] op_sel_hi:[1,0,1]
	v_exp_f32_e32 v198, v198
	v_exp_f32_e32 v199, v199
	v_exp_f32_e32 v200, v200
	v_exp_f32_e32 v201, v201
	v_exp_f32_e32 v202, v202
	v_exp_f32_e32 v203, v203
	v_exp_f32_e32 v244, v244
	v_exp_f32_e32 v245, v245
	v_pk_add_f32 v[198:199], v[198:199], v[254:255] op_sel_hi:[1,0]
	v_pk_add_f32 v[200:201], v[200:201], v[254:255] op_sel_hi:[1,0]
	v_pk_add_f32 v[202:203], v[202:203], v[254:255] op_sel_hi:[1,0]
	v_pk_add_f32 v[244:245], v[244:245], v[254:255] op_sel_hi:[1,0]
	v_rcp_f32_e32 v198, v198
	v_rcp_f32_e32 v199, v199
	v_rcp_f32_e32 v200, v200
	v_rcp_f32_e32 v201, v201
	v_rcp_f32_e32 v202, v202
	v_rcp_f32_e32 v203, v203
	v_rcp_f32_e32 v244, v244
	v_rcp_f32_e32 v245, v245
	v_pk_fma_f32 v[198:199], v[198:199], v[164:165], v[172:173]
	v_pk_fma_f32 v[200:201], v[200:201], v[166:167], v[174:175]
	v_pk_fma_f32 v[202:203], v[202:203], v[168:169], v[156:157]
	v_pk_fma_f32 v[244:245], v[244:245], v[170:171], v[246:247]
	v_cvt_pk_bf16_f32 v164, v198, v199
	v_cvt_pk_bf16_f32 v165, v200, v201
	v_cvt_pk_bf16_f32 v166, v202, v203
	v_cvt_pk_bf16_f32 v167, v244, v245
	global_store_dwordx4 v253, v[164:167], s[42:43]
	s_nop 0
	v_add_u32_e32 v253, 0x2000, v253
	s_branch .LBB0_1002

.Lmrg_P:
	v_mov_b32_e32 v172, 0
	v_mov_b32_e32 v173, 0
	v_mov_b32_e32 v174, 0
	v_mov_b32_e32 v175, 0
	v_mov_b32_e32 v156, 0
	v_mov_b32_e32 v157, 0
	v_mov_b32_e32 v246, 0
	v_mov_b32_e32 v247, 0
	global_load_dwordx4 v[144:147], v252, s[40:41]
	v_add_u32_e32 v252, 0x2000, v252
	global_load_dwordx4 v[152:155], v252, s[40:41]
	v_add_u32_e32 v252, 0x2000, v252
	global_load_dwordx4 v[212:215], v252, s[40:41]
	v_add_u32_e32 v252, 0x2000, v252
	global_load_dwordx4 v[220:223], v252, s[40:41]
	v_add_u32_e32 v252, 0x2000, v252
	s_waitcnt vmcnt(3)
	v_mul_f32_e32 v128, s45, v128
	v_mul_f32_e32 v129, s45, v129
	v_mul_f32_e32 v130, s45, v130
	v_mul_f32_e32 v131, s45, v131
	v_mul_f32_e32 v132, s45, v132
	v_mul_f32_e32 v133, s45, v133
	v_mul_f32_e32 v134, s45, v134
	v_mul_f32_e32 v135, s45, v135
	v_mul_f32_e32 v136, s45, v136
	v_mul_f32_e32 v137, s45, v137
	v_mul_f32_e32 v138, s45, v138
	v_mul_f32_e32 v139, s45, v139
	v_mul_f32_e32 v140, s45, v140
	v_mul_f32_e32 v141, s45, v141
	v_mul_f32_e32 v142, s45, v142
	v_mul_f32_e32 v143, s45, v143
	v_fmamk_f32 v239, v190, 0x3a800000, v228
	v_rsq_f32_e32 v238, v239
	v_lshlrev_b32_e32 v164, 16, v144
	v_and_b32_e32 v165, 0xffff0000, v144
	v_lshlrev_b32_e32 v166, 16, v145
	v_and_b32_e32 v167, 0xffff0000, v145
	v_lshlrev_b32_e32 v168, 16, v146
	v_and_b32_e32 v169, 0xffff0000, v146
	v_lshlrev_b32_e32 v170, 16, v147
	v_and_b32_e32 v171, 0xffff0000, v147
	v_mul_f32_e32 v238, s45, v238
	v_pk_fma_f32 v[198:199], v[124:125], v[238:239], v[140:141] op_sel_hi:[1,0,1]
	v_pk_fma_f32 v[200:201], v[126:127], v[238:239], v[142:143] op_sel_hi:[1,0,1]
	v_pk_fma_f32 v[202:203], v[120:121], v[238:239], v[136:137] op_sel_hi:[1,0,1]
	v_pk_fma_f32 v[244:245], v[122:123], v[238:239], v[138:139] op_sel_hi:[1,0,1]
	global_load_dwordx4 v[124:127], v252, s[40:41]
	v_add_u32_e32 v252, 0x2000, v252
	v_exp_f32_e32 v198, v198
	v_exp_f32_e32 v199, v199
	v_exp_f32_e32 v200, v200
	v_exp_f32_e32 v201, v201
	v_exp_f32_e32 v202, v202
	v_exp_f32_e32 v203, v203
	v_exp_f32_e32 v244, v244
	v_exp_f32_e32 v245, v245
	v_pk_add_f32 v[198:199], v[198:199], v[254:255] op_sel_hi:[1,0]
	v_pk_add_f32 v[200:201], v[200:201], v[254:255] op_sel_hi:[1,0]
	v_pk_add_f32 v[202:203], v[202:203], v[254:255] op_sel_hi:[1,0]
	v_pk_add_f32 v[244:245], v[244:245], v[254:255] op_sel_hi:[1,0]
	v_rcp_f32_e32 v198, v198
	v_rcp_f32_e32 v199, v199
	v_rcp_f32_e32 v200, v200
	v_rcp_f32_e32 v201, v201
	v_rcp_f32_e32 v202, v202
	v_rcp_f32_e32 v203, v203
	v_rcp_f32_e32 v244, v244
	v_rcp_f32_e32 v245, v245
	v_pk_fma_f32 v[198:199], v[198:199], v[164:165], v[172:173]
	v_pk_fma_f32 v[200:201], v[200:201], v[166:167], v[174:175]
	v_pk_fma_f32 v[164:165], v[202:203], v[168:169], v[156:157]
	v_pk_fma_f32 v[166:167], v[244:245], v[170:171], v[246:247]
	v_add_u32_e32 v253, 0x0, v255
	global_store_dwordx4 v253, v[198:201], s[4:5]
	global_store_dwordx4 v253, v[164:167], s[4:5] offset:64
	s_waitcnt vmcnt(5)
	v_fmamk_f32 v239, v191, 0x3a800000, v228
	v_rsq_f32_e32 v238, v239
	v_lshlrev_b32_e32 v164, 16, v152
	v_and_b32_e32 v165, 0xffff0000, v152
	v_lshlrev_b32_e32 v166, 16, v153
	v_and_b32_e32 v167, 0xffff0000, v153
	v_lshlrev_b32_e32 v168, 16, v154
	v_and_b32_e32 v169, 0xffff0000, v154
	v_lshlrev_b32_e32 v170, 16, v155
	v_and_b32_e32 v171, 0xffff0000, v155
	v_mul_f32_e32 v238, s45, v238
	v_pk_fma_f32 v[198:199], v[116:117], v[238:239], v[140:141] op_sel_hi:[1,0,1]
	v_pk_fma_f32 v[200:201], v[118:119], v[238:239], v[142:143] op_sel_hi:[1,0,1]
	v_pk_fma_f32 v[202:203], v[112:113], v[238:239], v[136:137] op_sel_hi:[1,0,1]
	v_pk_fma_f32 v[244:245], v[114:115], v[238:239], v[138:139] op_sel_hi:[1,0,1]
	global_load_dwordx4 v[116:119], v252, s[40:41]
	v_add_u32_e32 v252, 0x2000, v252
	v_exp_f32_e32 v198, v198
	v_exp_f32_e32 v199, v199
	v_exp_f32_e32 v200, v200
	v_exp_f32_e32 v201, v201
	v_exp_f32_e32 v202, v202
	v_exp_f32_e32 v203, v203
	v_exp_f32_e32 v244, v244
	v_exp_f32_e32 v245, v245
	v_pk_add_f32 v[198:199], v[198:199], v[254:255] op_sel_hi:[1,0]
	v_pk_add_f32 v[200:201], v[200:201], v[254:255] op_sel_hi:[1,0]
	v_pk_add_f32 v[202:203], v[202:203], v[254:255] op_sel_hi:[1,0]
	v_pk_add_f32 v[244:245], v[244:245], v[254:255] op_sel_hi:[1,0]
	v_rcp_f32_e32 v198, v198
	v_rcp_f32_e32 v199, v199
	v_rcp_f32_e32 v200, v200
	v_rcp_f32_e32 v201, v201
	v_rcp_f32_e32 v202, v202
	v_rcp_f32_e32 v203, v203
	v_rcp_f32_e32 v244, v244
	v_rcp_f32_e32 v245, v245
	v_pk_fma_f32 v[198:199], v[198:199], v[164:165], v[172:173]
	v_pk_fma_f32 v[200:201], v[200:201], v[166:167], v[174:175]
	v_pk_fma_f32 v[164:165], v[202:203], v[168:169], v[156:157]
	v_pk_fma_f32 v[166:167], v[244:245], v[170:171], v[246:247]
	v_add_u32_e32 v253, 0x10000, v255
	global_store_dwordx4 v253, v[198:201], s[4:5]
	global_store_dwordx4 v253, v[164:167], s[4:5] offset:64
	s_waitcnt vmcnt(7)
	v_fmamk_f32 v239, v192, 0x3a800000, v228
	v_rsq_f32_e32 v238, v239
	v_lshlrev_b32_e32 v164, 16, v212
	v_and_b32_e32 v165, 0xffff0000, v212
	v_lshlrev_b32_e32 v166, 16, v213
	v_and_b32_e32 v167, 0xffff0000, v213
	v_lshlrev_b32_e32 v168, 16, v214
	v_and_b32_e32 v169, 0xffff0000, v214
	v_lshlrev_b32_e32 v170, 16, v215
	v_and_b32_e32 v171, 0xffff0000, v215
	v_mul_f32_e32 v238, s45, v238
	v_pk_fma_f32 v[198:199], v[108:109], v[238:239], v[140:141] op_sel_hi:[1,0,1]
	v_pk_fma_f32 v[200:201], v[110:111], v[238:239], v[142:143] op_sel_hi:[1,0,1]
	v_pk_fma_f32 v[202:203], v[104:105], v[238:239], v[136:137] op_sel_hi:[1,0,1]
	v_pk_fma_f32 v[244:245], v[106:107], v[238:239], v[138:139] op_sel_hi:[1,0,1]
	global_load_dwordx4 v[108:111], v252, s[40:41]
	v_add_u32_e32 v252, 0x2000, v252
	v_exp_f32_e32 v198, v198
	v_exp_f32_e32 v199, v199
	v_exp_f32_e32 v200, v200
	v_exp_f32_e32 v201, v201
	v_exp_f32_e32 v202, v202
	v_exp_f32_e32 v203, v203
	v_exp_f32_e32 v244, v244
	v_exp_f32_e32 v245, v245
	v_pk_add_f32 v[198:199], v[198:199], v[254:255] op_sel_hi:[1,0]
	v_pk_add_f32 v[200:201], v[200:201], v[254:255] op_sel_hi:[1,0]
	v_pk_add_f32 v[202:203], v[202:203], v[254:255] op_sel_hi:[1,0]
	v_pk_add_f32 v[244:245], v[244:245], v[254:255] op_sel_hi:[1,0]
	v_rcp_f32_e32 v198, v198
	v_rcp_f32_e32 v199, v199
	v_rcp_f32_e32 v200, v200
	v_rcp_f32_e32 v201, v201
	v_rcp_f32_e32 v202, v202
	v_rcp_f32_e32 v203, v203
	v_rcp_f32_e32 v244, v244
	v_rcp_f32_e32 v245, v245
	v_pk_fma_f32 v[198:199], v[198:199], v[164:165], v[172:173]
	v_pk_fma_f32 v[200:201], v[200:201], v[166:167], v[174:175]
	v_pk_fma_f32 v[164:165], v[202:203], v[168:169], v[156:157]
	v_pk_fma_f32 v[166:167], v[244:245], v[170:171], v[246:247]
	v_add_u32_e32 v253, 0x20000, v255
	global_store_dwordx4 v253, v[198:201], s[4:5]
	global_store_dwordx4 v253, v[164:167], s[4:5] offset:64
	s_waitcnt vmcnt(9)
	v_fmamk_f32 v239, v193, 0x3a800000, v228
	v_rsq_f32_e32 v238, v239
	v_lshlrev_b32_e32 v164, 16, v220
	v_and_b32_e32 v165, 0xffff0000, v220
	v_lshlrev_b32_e32 v166, 16, v221
	v_and_b32_e32 v167, 0xffff0000, v221
	v_lshlrev_b32_e32 v168, 16, v222
	v_and_b32_e32 v169, 0xffff0000, v222
	v_lshlrev_b32_e32 v170, 16, v223
	v_and_b32_e32 v171, 0xffff0000, v223
	v_mul_f32_e32 v238, s45, v238
	v_pk_fma_f32 v[198:199], v[100:101], v[238:239], v[140:141] op_sel_hi:[1,0,1]
	v_pk_fma_f32 v[200:201], v[102:103], v[238:239], v[142:143] op_sel_hi:[1,0,1]
	v_pk_fma_f32 v[202:203], v[96:97], v[238:239], v[136:137] op_sel_hi:[1,0,1]
	v_pk_fma_f32 v[244:245], v[98:99], v[238:239], v[138:139] op_sel_hi:[1,0,1]
	global_load_dwordx4 v[100:103], v252, s[40:41]
	v_add_u32_e32 v252, 0x2000, v252
	v_exp_f32_e32 v198, v198
	v_exp_f32_e32 v199, v199
	v_exp_f32_e32 v200, v200
	v_exp_f32_e32 v201, v201
	v_exp_f32_e32 v202, v202
	v_exp_f32_e32 v203, v203
	v_exp_f32_e32 v244, v244
	v_exp_f32_e32 v245, v245
	v_pk_add_f32 v[198:199], v[198:199], v[254:255] op_sel_hi:[1,0]
	v_pk_add_f32 v[200:201], v[200:201], v[254:255] op_sel_hi:[1,0]
	v_pk_add_f32 v[202:203], v[202:203], v[254:255] op_sel_hi:[1,0]
	v_pk_add_f32 v[244:245], v[244:245], v[254:255] op_sel_hi:[1,0]
	v_rcp_f32_e32 v198, v198
	v_rcp_f32_e32 v199, v199
	v_rcp_f32_e32 v200, v200
	v_rcp_f32_e32 v201, v201
	v_rcp_f32_e32 v202, v202
	v_rcp_f32_e32 v203, v203
	v_rcp_f32_e32 v244, v244
	v_rcp_f32_e32 v245, v245
	v_pk_fma_f32 v[198:199], v[198:199], v[164:165], v[172:173]
	v_pk_fma_f32 v[200:201], v[200:201], v[166:167], v[174:175]
	v_pk_fma_f32 v[164:165], v[202:203], v[168:169], v[156:157]
	v_pk_fma_f32 v[166:167], v[244:245], v[170:171], v[246:247]
	v_add_u32_e32 v253, 0x30000, v255
	global_store_dwordx4 v253, v[198:201], s[4:5]
	global_store_dwordx4 v253, v[164:167], s[4:5] offset:64
	s_waitcnt vmcnt(11)
	v_fmamk_f32 v239, v190, 0x3a800000, v228
	v_rsq_f32_e32 v238, v239
	v_lshlrev_b32_e32 v164, 16, v124
	v_and_b32_e32 v165, 0xffff0000, v124
	v_lshlrev_b32_e32 v166, 16, v125
	v_and_b32_e32 v167, 0xffff0000, v125
	v_lshlrev_b32_e32 v168, 16, v126
	v_and_b32_e32 v169, 0xffff0000, v126
	v_lshlrev_b32_e32 v170, 16, v127
	v_and_b32_e32 v171, 0xffff0000, v127
	v_mul_f32_e32 v238, s45, v238
	v_pk_fma_f32 v[198:199], v[92:93], v[238:239], v[132:133] op_sel_hi:[1,0,1]
	v_pk_fma_f32 v[200:201], v[94:95], v[238:239], v[134:135] op_sel_hi:[1,0,1]
	v_pk_fma_f32 v[202:203], v[88:89], v[238:239], v[128:129] op_sel_hi:[1,0,1]
	v_pk_fma_f32 v[244:245], v[90:91], v[238:239], v[130:131] op_sel_hi:[1,0,1]
	global_load_dwordx4 v[92:95], v252, s[40:41]
	v_add_u32_e32 v252, 0x2000, v252
	v_exp_f32_e32 v198, v198
	v_exp_f32_e32 v199, v199
	v_exp_f32_e32 v200, v200
	v_exp_f32_e32 v201, v201
	v_exp_f32_e32 v202, v202
	v_exp_f32_e32 v203, v203
	v_exp_f32_e32 v244, v244
	v_exp_f32_e32 v245, v245
	v_pk_add_f32 v[198:199], v[198:199], v[254:255] op_sel_hi:[1,0]
	v_pk_add_f32 v[200:201], v[200:201], v[254:255] op_sel_hi:[1,0]
	v_pk_add_f32 v[202:203], v[202:203], v[254:255] op_sel_hi:[1,0]
	v_pk_add_f32 v[244:245], v[244:245], v[254:255] op_sel_hi:[1,0]
	v_rcp_f32_e32 v198, v198
	v_rcp_f32_e32 v199, v199
	v_rcp_f32_e32 v200, v200
	v_rcp_f32_e32 v201, v201
	v_rcp_f32_e32 v202, v202
	v_rcp_f32_e32 v203, v203
	v_rcp_f32_e32 v244, v244
	v_rcp_f32_e32 v245, v245
	v_pk_fma_f32 v[198:199], v[198:199], v[164:165], v[172:173]
	v_pk_fma_f32 v[200:201], v[200:201], v[166:167], v[174:175]
	v_pk_fma_f32 v[164:165], v[202:203], v[168:169], v[156:157]
	v_pk_fma_f32 v[166:167], v[244:245], v[170:171], v[246:247]
	v_add_u32_e32 v253, 0x200, v255
	global_store_dwordx4 v253, v[198:201], s[4:5]
	global_store_dwordx4 v253, v[164:167], s[4:5] offset:64
	s_waitcnt vmcnt(11)
	v_fmamk_f32 v239, v191, 0x3a800000, v228
	v_rsq_f32_e32 v238, v239
	v_lshlrev_b32_e32 v164, 16, v116
	v_and_b32_e32 v165, 0xffff0000, v116
	v_lshlrev_b32_e32 v166, 16, v117
	v_and_b32_e32 v167, 0xffff0000, v117
	v_lshlrev_b32_e32 v168, 16, v118
	v_and_b32_e32 v169, 0xffff0000, v118
	v_lshlrev_b32_e32 v170, 16, v119
	v_and_b32_e32 v171, 0xffff0000, v119
	v_mul_f32_e32 v238, s45, v238
	v_pk_fma_f32 v[198:199], v[84:85], v[238:239], v[132:133] op_sel_hi:[1,0,1]
	v_pk_fma_f32 v[200:201], v[86:87], v[238:239], v[134:135] op_sel_hi:[1,0,1]
	v_pk_fma_f32 v[202:203], v[80:81], v[238:239], v[128:129] op_sel_hi:[1,0,1]
	v_pk_fma_f32 v[244:245], v[82:83], v[238:239], v[130:131] op_sel_hi:[1,0,1]
	global_load_dwordx4 v[84:87], v252, s[40:41]
	v_add_u32_e32 v252, 0x2000, v252
	v_exp_f32_e32 v198, v198
	v_exp_f32_e32 v199, v199
	v_exp_f32_e32 v200, v200
	v_exp_f32_e32 v201, v201
	v_exp_f32_e32 v202, v202
	v_exp_f32_e32 v203, v203
	v_exp_f32_e32 v244, v244
	v_exp_f32_e32 v245, v245
	v_pk_add_f32 v[198:199], v[198:199], v[254:255] op_sel_hi:[1,0]
	v_pk_add_f32 v[200:201], v[200:201], v[254:255] op_sel_hi:[1,0]
	v_pk_add_f32 v[202:203], v[202:203], v[254:255] op_sel_hi:[1,0]
	v_pk_add_f32 v[244:245], v[244:245], v[254:255] op_sel_hi:[1,0]
	v_rcp_f32_e32 v198, v198
	v_rcp_f32_e32 v199, v199
	v_rcp_f32_e32 v200, v200
	v_rcp_f32_e32 v201, v201
	v_rcp_f32_e32 v202, v202
	v_rcp_f32_e32 v203, v203
	v_rcp_f32_e32 v244, v244
	v_rcp_f32_e32 v245, v245
	v_pk_fma_f32 v[198:199], v[198:199], v[164:165], v[172:173]
	v_pk_fma_f32 v[200:201], v[200:201], v[166:167], v[174:175]
	v_pk_fma_f32 v[164:165], v[202:203], v[168:169], v[156:157]
	v_pk_fma_f32 v[166:167], v[244:245], v[170:171], v[246:247]
	v_add_u32_e32 v253, 0x10200, v255
	global_store_dwordx4 v253, v[198:201], s[4:5]
	global_store_dwordx4 v253, v[164:167], s[4:5] offset:64
	s_waitcnt vmcnt(11)
	v_fmamk_f32 v239, v192, 0x3a800000, v228
	v_rsq_f32_e32 v238, v239
	v_lshlrev_b32_e32 v164, 16, v108
	v_and_b32_e32 v165, 0xffff0000, v108
	v_lshlrev_b32_e32 v166, 16, v109
	v_and_b32_e32 v167, 0xffff0000, v109
	v_lshlrev_b32_e32 v168, 16, v110
	v_and_b32_e32 v169, 0xffff0000, v110
	v_lshlrev_b32_e32 v170, 16, v111
	v_and_b32_e32 v171, 0xffff0000, v111
	v_mul_f32_e32 v238, s45, v238
	v_pk_fma_f32 v[198:199], v[76:77], v[238:239], v[132:133] op_sel_hi:[1,0,1]
	v_pk_fma_f32 v[200:201], v[78:79], v[238:239], v[134:135] op_sel_hi:[1,0,1]
	v_pk_fma_f32 v[202:203], v[72:73], v[238:239], v[128:129] op_sel_hi:[1,0,1]
	v_pk_fma_f32 v[244:245], v[74:75], v[238:239], v[130:131] op_sel_hi:[1,0,1]
	global_load_dwordx4 v[76:79], v252, s[40:41]
	v_add_u32_e32 v252, 0x2000, v252
	v_exp_f32_e32 v198, v198
	v_exp_f32_e32 v199, v199
	v_exp_f32_e32 v200, v200
	v_exp_f32_e32 v201, v201
	v_exp_f32_e32 v202, v202
	v_exp_f32_e32 v203, v203
	v_exp_f32_e32 v244, v244
	v_exp_f32_e32 v245, v245
	v_pk_add_f32 v[198:199], v[198:199], v[254:255] op_sel_hi:[1,0]
	v_pk_add_f32 v[200:201], v[200:201], v[254:255] op_sel_hi:[1,0]
	v_pk_add_f32 v[202:203], v[202:203], v[254:255] op_sel_hi:[1,0]
	v_pk_add_f32 v[244:245], v[244:245], v[254:255] op_sel_hi:[1,0]
	v_rcp_f32_e32 v198, v198
	v_rcp_f32_e32 v199, v199
	v_rcp_f32_e32 v200, v200
	v_rcp_f32_e32 v201, v201
	v_rcp_f32_e32 v202, v202
	v_rcp_f32_e32 v203, v203
	v_rcp_f32_e32 v244, v244
	v_rcp_f32_e32 v245, v245
	v_pk_fma_f32 v[198:199], v[198:199], v[164:165], v[172:173]
	v_pk_fma_f32 v[200:201], v[200:201], v[166:167], v[174:175]
	v_pk_fma_f32 v[164:165], v[202:203], v[168:169], v[156:157]
	v_pk_fma_f32 v[166:167], v[244:245], v[170:171], v[246:247]
	v_add_u32_e32 v253, 0x20200, v255
	global_store_dwordx4 v253, v[198:201], s[4:5]
	global_store_dwordx4 v253, v[164:167], s[4:5] offset:64
	s_waitcnt vmcnt(11)
	v_fmamk_f32 v239, v193, 0x3a800000, v228
	v_rsq_f32_e32 v238, v239
	v_lshlrev_b32_e32 v164, 16, v100
	v_and_b32_e32 v165, 0xffff0000, v100
	v_lshlrev_b32_e32 v166, 16, v101
	v_and_b32_e32 v167, 0xffff0000, v101
	v_lshlrev_b32_e32 v168, 16, v102
	v_and_b32_e32 v169, 0xffff0000, v102
	v_lshlrev_b32_e32 v170, 16, v103
	v_and_b32_e32 v171, 0xffff0000, v103
	v_mul_f32_e32 v238, s45, v238
	v_pk_fma_f32 v[198:199], v[68:69], v[238:239], v[132:133] op_sel_hi:[1,0,1]
	v_pk_fma_f32 v[200:201], v[70:71], v[238:239], v[134:135] op_sel_hi:[1,0,1]
	v_pk_fma_f32 v[202:203], v[64:65], v[238:239], v[128:129] op_sel_hi:[1,0,1]
	v_pk_fma_f32 v[244:245], v[66:67], v[238:239], v[130:131] op_sel_hi:[1,0,1]
	global_load_dwordx4 v[68:71], v252, s[40:41]
	v_add_u32_e32 v252, 0x2000, v252
	v_exp_f32_e32 v198, v198
	v_exp_f32_e32 v199, v199
	v_exp_f32_e32 v200, v200
	v_exp_f32_e32 v201, v201
	v_exp_f32_e32 v202, v202
	v_exp_f32_e32 v203, v203
	v_exp_f32_e32 v244, v244
	v_exp_f32_e32 v245, v245
	v_pk_add_f32 v[198:199], v[198:199], v[254:255] op_sel_hi:[1,0]
	v_pk_add_f32 v[200:201], v[200:201], v[254:255] op_sel_hi:[1,0]
	v_pk_add_f32 v[202:203], v[202:203], v[254:255] op_sel_hi:[1,0]
	v_pk_add_f32 v[244:245], v[244:245], v[254:255] op_sel_hi:[1,0]
	v_rcp_f32_e32 v198, v198
	v_rcp_f32_e32 v199, v199
	v_rcp_f32_e32 v200, v200
	v_rcp_f32_e32 v201, v201
	v_rcp_f32_e32 v202, v202
	v_rcp_f32_e32 v203, v203
	v_rcp_f32_e32 v244, v244
	v_rcp_f32_e32 v245, v245
	v_pk_fma_f32 v[198:199], v[198:199], v[164:165], v[172:173]
	v_pk_fma_f32 v[200:201], v[200:201], v[166:167], v[174:175]
	v_pk_fma_f32 v[164:165], v[202:203], v[168:169], v[156:157]
	v_pk_fma_f32 v[166:167], v[244:245], v[170:171], v[246:247]
	v_add_u32_e32 v253, 0x30200, v255
	global_store_dwordx4 v253, v[198:201], s[4:5]
	global_store_dwordx4 v253, v[164:167], s[4:5] offset:64
	s_waitcnt vmcnt(11)
	v_fmamk_f32 v239, v194, 0x3a800000, v228
	v_rsq_f32_e32 v238, v239
	v_lshlrev_b32_e32 v164, 16, v92
	v_and_b32_e32 v165, 0xffff0000, v92
	v_lshlrev_b32_e32 v166, 16, v93
	v_and_b32_e32 v167, 0xffff0000, v93
	v_lshlrev_b32_e32 v168, 16, v94
	v_and_b32_e32 v169, 0xffff0000, v94
	v_lshlrev_b32_e32 v170, 16, v95
	v_and_b32_e32 v171, 0xffff0000, v95
	v_mul_f32_e32 v238, s45, v238
	v_pk_fma_f32 v[198:199], v[60:61], v[238:239], v[140:141] op_sel_hi:[1,0,1]
	v_pk_fma_f32 v[200:201], v[62:63], v[238:239], v[142:143] op_sel_hi:[1,0,1]
	v_pk_fma_f32 v[202:203], v[56:57], v[238:239], v[136:137] op_sel_hi:[1,0,1]
	v_pk_fma_f32 v[244:245], v[58:59], v[238:239], v[138:139] op_sel_hi:[1,0,1]
	global_load_dwordx4 v[60:63], v252, s[40:41]
	v_add_u32_e32 v252, 0x2000, v252
	v_exp_f32_e32 v198, v198
	v_exp_f32_e32 v199, v199
	v_exp_f32_e32 v200, v200
	v_exp_f32_e32 v201, v201
	v_exp_f32_e32 v202, v202
	v_exp_f32_e32 v203, v203
	v_exp_f32_e32 v244, v244
	v_exp_f32_e32 v245, v245
	v_pk_add_f32 v[198:199], v[198:199], v[254:255] op_sel_hi:[1,0]
	v_pk_add_f32 v[200:201], v[200:201], v[254:255] op_sel_hi:[1,0]
	v_pk_add_f32 v[202:203], v[202:203], v[254:255] op_sel_hi:[1,0]
	v_pk_add_f32 v[244:245], v[244:245], v[254:255] op_sel_hi:[1,0]
	v_rcp_f32_e32 v198, v198
	v_rcp_f32_e32 v199, v199
	v_rcp_f32_e32 v200, v200
	v_rcp_f32_e32 v201, v201
	v_rcp_f32_e32 v202, v202
	v_rcp_f32_e32 v203, v203
	v_rcp_f32_e32 v244, v244
	v_rcp_f32_e32 v245, v245
	v_pk_fma_f32 v[198:199], v[198:199], v[164:165], v[172:173]
	v_pk_fma_f32 v[200:201], v[200:201], v[166:167], v[174:175]
	v_pk_fma_f32 v[164:165], v[202:203], v[168:169], v[156:157]
	v_pk_fma_f32 v[166:167], v[244:245], v[170:171], v[246:247]
	v_add_u32_e32 v253, 0x80000, v255
	global_store_dwordx4 v253, v[198:201], s[4:5]
	global_store_dwordx4 v253, v[164:167], s[4:5] offset:64
	s_waitcnt vmcnt(11)
	v_fmamk_f32 v239, v195, 0x3a800000, v228
	v_rsq_f32_e32 v238, v239
	v_lshlrev_b32_e32 v164, 16, v84
	v_and_b32_e32 v165, 0xffff0000, v84
	v_lshlrev_b32_e32 v166, 16, v85
	v_and_b32_e32 v167, 0xffff0000, v85
	v_lshlrev_b32_e32 v168, 16, v86
	v_and_b32_e32 v169, 0xffff0000, v86
	v_lshlrev_b32_e32 v170, 16, v87
	v_and_b32_e32 v171, 0xffff0000, v87
	v_mul_f32_e32 v238, s45, v238
	v_pk_fma_f32 v[198:199], v[52:53], v[238:239], v[140:141] op_sel_hi:[1,0,1]
	v_pk_fma_f32 v[200:201], v[54:55], v[238:239], v[142:143] op_sel_hi:[1,0,1]
	v_pk_fma_f32 v[202:203], v[48:49], v[238:239], v[136:137] op_sel_hi:[1,0,1]
	v_pk_fma_f32 v[244:245], v[50:51], v[238:239], v[138:139] op_sel_hi:[1,0,1]
	global_load_dwordx4 v[52:55], v252, s[40:41]
	v_add_u32_e32 v252, 0x2000, v252
	v_exp_f32_e32 v198, v198
	v_exp_f32_e32 v199, v199
	v_exp_f32_e32 v200, v200
	v_exp_f32_e32 v201, v201
	v_exp_f32_e32 v202, v202
	v_exp_f32_e32 v203, v203
	v_exp_f32_e32 v244, v244
	v_exp_f32_e32 v245, v245
	v_pk_add_f32 v[198:199], v[198:199], v[254:255] op_sel_hi:[1,0]
	v_pk_add_f32 v[200:201], v[200:201], v[254:255] op_sel_hi:[1,0]
	v_pk_add_f32 v[202:203], v[202:203], v[254:255] op_sel_hi:[1,0]
	v_pk_add_f32 v[244:245], v[244:245], v[254:255] op_sel_hi:[1,0]
	v_rcp_f32_e32 v198, v198
	v_rcp_f32_e32 v199, v199
	v_rcp_f32_e32 v200, v200
	v_rcp_f32_e32 v201, v201
	v_rcp_f32_e32 v202, v202
	v_rcp_f32_e32 v203, v203
	v_rcp_f32_e32 v244, v244
	v_rcp_f32_e32 v245, v245
	v_pk_fma_f32 v[198:199], v[198:199], v[164:165], v[172:173]
	v_pk_fma_f32 v[200:201], v[200:201], v[166:167], v[174:175]
	v_pk_fma_f32 v[164:165], v[202:203], v[168:169], v[156:157]
	v_pk_fma_f32 v[166:167], v[244:245], v[170:171], v[246:247]
	v_add_u32_e32 v253, 0x90000, v255
	global_store_dwordx4 v253, v[198:201], s[4:5]
	global_store_dwordx4 v253, v[164:167], s[4:5] offset:64
	s_waitcnt vmcnt(11)
	v_fmamk_f32 v239, v196, 0x3a800000, v228
	v_rsq_f32_e32 v238, v239
	v_lshlrev_b32_e32 v164, 16, v76
	v_and_b32_e32 v165, 0xffff0000, v76
	v_lshlrev_b32_e32 v166, 16, v77
	v_and_b32_e32 v167, 0xffff0000, v77
	v_lshlrev_b32_e32 v168, 16, v78
	v_and_b32_e32 v169, 0xffff0000, v78
	v_lshlrev_b32_e32 v170, 16, v79
	v_and_b32_e32 v171, 0xffff0000, v79
	v_mul_f32_e32 v238, s45, v238
	v_pk_fma_f32 v[198:199], v[44:45], v[238:239], v[140:141] op_sel_hi:[1,0,1]
	v_pk_fma_f32 v[200:201], v[46:47], v[238:239], v[142:143] op_sel_hi:[1,0,1]
	v_pk_fma_f32 v[202:203], v[40:41], v[238:239], v[136:137] op_sel_hi:[1,0,1]
	v_pk_fma_f32 v[244:245], v[42:43], v[238:239], v[138:139] op_sel_hi:[1,0,1]
	global_load_dwordx4 v[44:47], v252, s[40:41]
	v_add_u32_e32 v252, 0x2000, v252
	v_exp_f32_e32 v198, v198
	v_exp_f32_e32 v199, v199
	v_exp_f32_e32 v200, v200
	v_exp_f32_e32 v201, v201
	v_exp_f32_e32 v202, v202
	v_exp_f32_e32 v203, v203
	v_exp_f32_e32 v244, v244
	v_exp_f32_e32 v245, v245
	v_pk_add_f32 v[198:199], v[198:199], v[254:255] op_sel_hi:[1,0]
	v_pk_add_f32 v[200:201], v[200:201], v[254:255] op_sel_hi:[1,0]
	v_pk_add_f32 v[202:203], v[202:203], v[254:255] op_sel_hi:[1,0]
	v_pk_add_f32 v[244:245], v[244:245], v[254:255] op_sel_hi:[1,0]
	v_rcp_f32_e32 v198, v198
	v_rcp_f32_e32 v199, v199
	v_rcp_f32_e32 v200, v200
	v_rcp_f32_e32 v201, v201
	v_rcp_f32_e32 v202, v202
	v_rcp_f32_e32 v203, v203
	v_rcp_f32_e32 v244, v244
	v_rcp_f32_e32 v245, v245
	v_pk_fma_f32 v[198:199], v[198:199], v[164:165], v[172:173]
	v_pk_fma_f32 v[200:201], v[200:201], v[166:167], v[174:175]
	v_pk_fma_f32 v[164:165], v[202:203], v[168:169], v[156:157]
	v_pk_fma_f32 v[166:167], v[244:245], v[170:171], v[246:247]
	v_add_u32_e32 v253, 0xa0000, v255
	global_store_dwordx4 v253, v[198:201], s[4:5]
	global_store_dwordx4 v253, v[164:167], s[4:5] offset:64
	s_waitcnt vmcnt(11)
	v_fmamk_f32 v239, v197, 0x3a800000, v228
	v_rsq_f32_e32 v238, v239
	v_lshlrev_b32_e32 v164, 16, v68
	v_and_b32_e32 v165, 0xffff0000, v68
	v_lshlrev_b32_e32 v166, 16, v69
	v_and_b32_e32 v167, 0xffff0000, v69
	v_lshlrev_b32_e32 v168, 16, v70
	v_and_b32_e32 v169, 0xffff0000, v70
	v_lshlrev_b32_e32 v170, 16, v71
	v_and_b32_e32 v171, 0xffff0000, v71
	v_mul_f32_e32 v238, s45, v238
	v_pk_fma_f32 v[198:199], v[36:37], v[238:239], v[140:141] op_sel_hi:[1,0,1]
	v_pk_fma_f32 v[200:201], v[38:39], v[238:239], v[142:143] op_sel_hi:[1,0,1]
	v_pk_fma_f32 v[202:203], v[32:33], v[238:239], v[136:137] op_sel_hi:[1,0,1]
	v_pk_fma_f32 v[244:245], v[34:35], v[238:239], v[138:139] op_sel_hi:[1,0,1]
	global_load_dwordx4 v[36:39], v252, s[40:41]
	v_add_u32_e32 v252, 0x2000, v252
	v_exp_f32_e32 v198, v198
	v_exp_f32_e32 v199, v199
	v_exp_f32_e32 v200, v200
	v_exp_f32_e32 v201, v201
	v_exp_f32_e32 v202, v202
	v_exp_f32_e32 v203, v203
	v_exp_f32_e32 v244, v244
	v_exp_f32_e32 v245, v245
	v_pk_add_f32 v[198:199], v[198:199], v[254:255] op_sel_hi:[1,0]
	v_pk_add_f32 v[200:201], v[200:201], v[254:255] op_sel_hi:[1,0]
	v_pk_add_f32 v[202:203], v[202:203], v[254:255] op_sel_hi:[1,0]
	v_pk_add_f32 v[244:245], v[244:245], v[254:255] op_sel_hi:[1,0]
	v_rcp_f32_e32 v198, v198
	v_rcp_f32_e32 v199, v199
	v_rcp_f32_e32 v200, v200
	v_rcp_f32_e32 v201, v201
	v_rcp_f32_e32 v202, v202
	v_rcp_f32_e32 v203, v203
	v_rcp_f32_e32 v244, v244
	v_rcp_f32_e32 v245, v245
	v_pk_fma_f32 v[198:199], v[198:199], v[164:165], v[172:173]
	v_pk_fma_f32 v[200:201], v[200:201], v[166:167], v[174:175]
	v_pk_fma_f32 v[164:165], v[202:203], v[168:169], v[156:157]
	v_pk_fma_f32 v[166:167], v[244:245], v[170:171], v[246:247]
	v_add_u32_e32 v253, 0xb0000, v255
	global_store_dwordx4 v253, v[198:201], s[4:5]
	global_store_dwordx4 v253, v[164:167], s[4:5] offset:64
	s_waitcnt vmcnt(11)
	v_fmamk_f32 v239, v194, 0x3a800000, v228
	v_rsq_f32_e32 v238, v239
	v_lshlrev_b32_e32 v164, 16, v60
	v_and_b32_e32 v165, 0xffff0000, v60
	v_lshlrev_b32_e32 v166, 16, v61
	v_and_b32_e32 v167, 0xffff0000, v61
	v_lshlrev_b32_e32 v168, 16, v62
	v_and_b32_e32 v169, 0xffff0000, v62
	v_lshlrev_b32_e32 v170, 16, v63
	v_and_b32_e32 v171, 0xffff0000, v63
	v_mul_f32_e32 v238, s45, v238
	v_pk_fma_f32 v[198:199], v[28:29], v[238:239], v[132:133] op_sel_hi:[1,0,1]
	v_pk_fma_f32 v[200:201], v[30:31], v[238:239], v[134:135] op_sel_hi:[1,0,1]
	v_pk_fma_f32 v[202:203], v[24:25], v[238:239], v[128:129] op_sel_hi:[1,0,1]
	v_pk_fma_f32 v[244:245], v[26:27], v[238:239], v[130:131] op_sel_hi:[1,0,1]
	v_exp_f32_e32 v198, v198
	v_exp_f32_e32 v199, v199
	v_exp_f32_e32 v200, v200
	v_exp_f32_e32 v201, v201
	v_exp_f32_e32 v202, v202
	v_exp_f32_e32 v203, v203
	v_exp_f32_e32 v244, v244
	v_exp_f32_e32 v245, v245
	v_pk_add_f32 v[198:199], v[198:199], v[254:255] op_sel_hi:[1,0]
	v_pk_add_f32 v[200:201], v[200:201], v[254:255] op_sel_hi:[1,0]
	v_pk_add_f32 v[202:203], v[202:203], v[254:255] op_sel_hi:[1,0]
	v_pk_add_f32 v[244:245], v[244:245], v[254:255] op_sel_hi:[1,0]
	v_rcp_f32_e32 v198, v198
	v_rcp_f32_e32 v199, v199
	v_rcp_f32_e32 v200, v200
	v_rcp_f32_e32 v201, v201
	v_rcp_f32_e32 v202, v202
	v_rcp_f32_e32 v203, v203
	v_rcp_f32_e32 v244, v244
	v_rcp_f32_e32 v245, v245
	v_pk_fma_f32 v[198:199], v[198:199], v[164:165], v[172:173]
	v_pk_fma_f32 v[200:201], v[200:201], v[166:167], v[174:175]
	v_pk_fma_f32 v[164:165], v[202:203], v[168:169], v[156:157]
	v_pk_fma_f32 v[166:167], v[244:245], v[170:171], v[246:247]
	v_add_u32_e32 v253, 0x80200, v255
	global_store_dwordx4 v253, v[198:201], s[4:5]
	global_store_dwordx4 v253, v[164:167], s[4:5] offset:64
	s_waitcnt vmcnt(10)
	v_fmamk_f32 v239, v195, 0x3a800000, v228
	v_rsq_f32_e32 v238, v239
	v_lshlrev_b32_e32 v164, 16, v52
	v_and_b32_e32 v165, 0xffff0000, v52
	v_lshlrev_b32_e32 v166, 16, v53
	v_and_b32_e32 v167, 0xffff0000, v53
	v_lshlrev_b32_e32 v168, 16, v54
	v_and_b32_e32 v169, 0xffff0000, v54
	v_lshlrev_b32_e32 v170, 16, v55
	v_and_b32_e32 v171, 0xffff0000, v55
	v_mul_f32_e32 v238, s45, v238
	v_pk_fma_f32 v[198:199], v[20:21], v[238:239], v[132:133] op_sel_hi:[1,0,1]
	v_pk_fma_f32 v[200:201], v[22:23], v[238:239], v[134:135] op_sel_hi:[1,0,1]
	v_pk_fma_f32 v[202:203], v[16:17], v[238:239], v[128:129] op_sel_hi:[1,0,1]
	v_pk_fma_f32 v[244:245], v[18:19], v[238:239], v[130:131] op_sel_hi:[1,0,1]
	v_exp_f32_e32 v198, v198
	v_exp_f32_e32 v199, v199
	v_exp_f32_e32 v200, v200
	v_exp_f32_e32 v201, v201
	v_exp_f32_e32 v202, v202
	v_exp_f32_e32 v203, v203
	v_exp_f32_e32 v244, v244
	v_exp_f32_e32 v245, v245
	v_pk_add_f32 v[198:199], v[198:199], v[254:255] op_sel_hi:[1,0]
	v_pk_add_f32 v[200:201], v[200:201], v[254:255] op_sel_hi:[1,0]
	v_pk_add_f32 v[202:203], v[202:203], v[254:255] op_sel_hi:[1,0]
	v_pk_add_f32 v[244:245], v[244:245], v[254:255] op_sel_hi:[1,0]
	v_rcp_f32_e32 v198, v198
	v_rcp_f32_e32 v199, v199
	v_rcp_f32_e32 v200, v200
	v_rcp_f32_e32 v201, v201
	v_rcp_f32_e32 v202, v202
	v_rcp_f32_e32 v203, v203
	v_rcp_f32_e32 v244, v244
	v_rcp_f32_e32 v245, v245
	v_pk_fma_f32 v[198:199], v[198:199], v[164:165], v[172:173]
	v_pk_fma_f32 v[200:201], v[200:201], v[166:167], v[174:175]
	v_pk_fma_f32 v[164:165], v[202:203], v[168:169], v[156:157]
	v_pk_fma_f32 v[166:167], v[244:245], v[170:171], v[246:247]
	v_add_u32_e32 v253, 0x90200, v255
	global_store_dwordx4 v253, v[198:201], s[4:5]
	global_store_dwordx4 v253, v[164:167], s[4:5] offset:64
	s_waitcnt vmcnt(9)
	v_fmamk_f32 v239, v196, 0x3a800000, v228
	v_rsq_f32_e32 v238, v239
	v_lshlrev_b32_e32 v164, 16, v44
	v_and_b32_e32 v165, 0xffff0000, v44
	v_lshlrev_b32_e32 v166, 16, v45
	v_and_b32_e32 v167, 0xffff0000, v45
	v_lshlrev_b32_e32 v168, 16, v46
	v_and_b32_e32 v169, 0xffff0000, v46
	v_lshlrev_b32_e32 v170, 16, v47
	v_and_b32_e32 v171, 0xffff0000, v47
	v_mul_f32_e32 v238, s45, v238
	v_pk_fma_f32 v[198:199], v[12:13], v[238:239], v[132:133] op_sel_hi:[1,0,1]
	v_pk_fma_f32 v[200:201], v[14:15], v[238:239], v[134:135] op_sel_hi:[1,0,1]
	v_pk_fma_f32 v[202:203], v[8:9], v[238:239], v[128:129] op_sel_hi:[1,0,1]
	v_pk_fma_f32 v[244:245], v[10:11], v[238:239], v[130:131] op_sel_hi:[1,0,1]
	v_exp_f32_e32 v198, v198
	v_exp_f32_e32 v199, v199
	v_exp_f32_e32 v200, v200
	v_exp_f32_e32 v201, v201
	v_exp_f32_e32 v202, v202
	v_exp_f32_e32 v203, v203
	v_exp_f32_e32 v244, v244
	v_exp_f32_e32 v245, v245
	v_pk_add_f32 v[198:199], v[198:199], v[254:255] op_sel_hi:[1,0]
	v_pk_add_f32 v[200:201], v[200:201], v[254:255] op_sel_hi:[1,0]
	v_pk_add_f32 v[202:203], v[202:203], v[254:255] op_sel_hi:[1,0]
	v_pk_add_f32 v[244:245], v[244:245], v[254:255] op_sel_hi:[1,0]
	v_rcp_f32_e32 v198, v198
	v_rcp_f32_e32 v199, v199
	v_rcp_f32_e32 v200, v200
	v_rcp_f32_e32 v201, v201
	v_rcp_f32_e32 v202, v202
	v_rcp_f32_e32 v203, v203
	v_rcp_f32_e32 v244, v244
	v_rcp_f32_e32 v245, v245
	v_pk_fma_f32 v[198:199], v[198:199], v[164:165], v[172:173]
	v_pk_fma_f32 v[200:201], v[200:201], v[166:167], v[174:175]
	v_pk_fma_f32 v[164:165], v[202:203], v[168:169], v[156:157]
	v_pk_fma_f32 v[166:167], v[244:245], v[170:171], v[246:247]
	v_add_u32_e32 v253, 0xa0200, v255
	global_store_dwordx4 v253, v[198:201], s[4:5]
	global_store_dwordx4 v253, v[164:167], s[4:5] offset:64
	s_waitcnt vmcnt(8)
	v_fmamk_f32 v239, v197, 0x3a800000, v228
	v_rsq_f32_e32 v238, v239
	v_lshlrev_b32_e32 v164, 16, v36
	v_and_b32_e32 v165, 0xffff0000, v36
	v_lshlrev_b32_e32 v166, 16, v37
	v_and_b32_e32 v167, 0xffff0000, v37
	v_lshlrev_b32_e32 v168, 16, v38
	v_and_b32_e32 v169, 0xffff0000, v38
	v_lshlrev_b32_e32 v170, 16, v39
	v_and_b32_e32 v171, 0xffff0000, v39
	v_mul_f32_e32 v238, s45, v238
	v_pk_fma_f32 v[198:199], v[4:5], v[238:239], v[132:133] op_sel_hi:[1,0,1]
	v_pk_fma_f32 v[200:201], v[6:7], v[238:239], v[134:135] op_sel_hi:[1,0,1]
	v_pk_fma_f32 v[202:203], v[0:1], v[238:239], v[128:129] op_sel_hi:[1,0,1]
	v_pk_fma_f32 v[244:245], v[2:3], v[238:239], v[130:131] op_sel_hi:[1,0,1]
	v_exp_f32_e32 v198, v198
	v_exp_f32_e32 v199, v199
	v_exp_f32_e32 v200, v200
	v_exp_f32_e32 v201, v201
	v_exp_f32_e32 v202, v202
	v_exp_f32_e32 v203, v203
	v_exp_f32_e32 v244, v244
	v_exp_f32_e32 v245, v245
	v_pk_add_f32 v[198:199], v[198:199], v[254:255] op_sel_hi:[1,0]
	v_pk_add_f32 v[200:201], v[200:201], v[254:255] op_sel_hi:[1,0]
	v_pk_add_f32 v[202:203], v[202:203], v[254:255] op_sel_hi:[1,0]
	v_pk_add_f32 v[244:245], v[244:245], v[254:255] op_sel_hi:[1,0]
	v_rcp_f32_e32 v198, v198
	v_rcp_f32_e32 v199, v199
	v_rcp_f32_e32 v200, v200
	v_rcp_f32_e32 v201, v201
	v_rcp_f32_e32 v202, v202
	v_rcp_f32_e32 v203, v203
	v_rcp_f32_e32 v244, v244
	v_rcp_f32_e32 v245, v245
	v_pk_fma_f32 v[198:199], v[198:199], v[164:165], v[172:173]
	v_pk_fma_f32 v[200:201], v[200:201], v[166:167], v[174:175]
	v_pk_fma_f32 v[164:165], v[202:203], v[168:169], v[156:157]
	v_pk_fma_f32 v[166:167], v[244:245], v[170:171], v[246:247]
	v_add_u32_e32 v253, 0xb0200, v255
	global_store_dwordx4 v253, v[198:201], s[4:5]
	global_store_dwordx4 v253, v[164:167], s[4:5] offset:64
	s_branch .LBB0_1002
